# redundant lgkmcnt(0) wait after the pre-MFMA barrier removed from the three large GEMM loops (counter already drained before the barrier)
# baseline (speedup 1.0000x reference)
.Lprio_mi:
	s_add_u32 s50, s46, 0x100
	s_addc_u32 s51, s47, 0
	s_add_u32 s3, s46, 0xfffff900
	s_addc_u32 s33, s47, -1
	s_cmp_gt_u32 s50, 0x7ff
	s_cselect_b32 s50, s3, s50
	s_cselect_b32 s51, s33, s51
	s_add_u32 s3, s92, s50
	s_addc_u32 s33, s93, s51
	s_add_u32 s43, s36, s50
	s_addc_u32 s54, s37, s51
	s_add_i32 s69, 0, 0x10000
	s_cmp_eq_u32 s31, 12
	s_cselect_b32 s97, s7, s33
	s_cselect_b32 s96, s11, s3
	s_cselect_b32 s95, s0, s54
	s_cselect_b32 s94, s29, s43
	s_add_i32 s3, 0, 0x14000
	ds_read_b128 v[40:43], v224
	ds_read_b128 v[60:63], v224 offset:1024
	ds_read_b128 v[80:83], v224 offset:2048
	ds_read_b128 v[100:103], v224 offset:3072
	ds_read_b128 v[120:123], v224 offset:16384
	ds_read_b128 v[140:143], v224 offset:17408
	ds_read_b128 v[152:155], v224 offset:18432
	ds_read_b128 v[168:171], v224 offset:19456
	s_add_u32 s33, s92, s46
	s_addc_u32 s43, s93, s47
	s_add_u32 s46, s33, 0x40080
	s_addc_u32 s47, s43, 0
	s_add_i32 m0, s23, 0xc000
	ds_read_b128 v[172:175], v202
	ds_read_b128 v[176:179], v202 offset:1024
	ds_read_b128 v[180:183], v202 offset:2048
	ds_read_b128 v[204:207], v202 offset:3072
	ds_read_b128 v[208:211], v202 offset:4096
	ds_read_b128 v[212:215], v202 offset:5120
	ds_read_b128 v[216:219], v202 offset:6144
	ds_read_b128 v[220:223], v202 offset:7168
	global_load_lds_dwordx4 v156, s[46:47]
	s_add_i32 m0, s23, 0xe000
	s_nop 0
	global_load_lds_dwordx4 v160, s[46:47]
	s_waitcnt vmcnt(8)
	s_waitcnt lgkmcnt(0)
	s_barrier
	v_mfma_f32_16x16x32_bf16 v[148:151], v[40:43], v[172:175], 0
	v_mfma_f32_16x16x32_bf16 v[144:147], v[80:83], v[172:175], 0
	v_mfma_f32_16x16x32_bf16 v[128:131], v[40:43], v[180:183], 0
	v_mfma_f32_16x16x32_bf16 v[124:127], v[80:83], v[180:183], 0
	v_mfma_f32_16x16x32_bf16 v[108:111], v[40:43], v[208:211], 0
	v_mfma_f32_16x16x32_bf16 v[104:107], v[80:83], v[208:211], 0
	v_mfma_f32_16x16x32_bf16 v[88:91], v[40:43], v[216:219], 0
	v_mfma_f32_16x16x32_bf16 v[84:87], v[80:83], v[216:219], 0
	v_mfma_f32_16x16x32_bf16 v[148:151], v[60:63], v[176:179], v[148:151]
	v_mfma_f32_16x16x32_bf16 v[144:147], v[100:103], v[176:179], v[144:147]
	v_mfma_f32_16x16x32_bf16 v[128:131], v[60:63], v[204:207], v[128:131]
	v_mfma_f32_16x16x32_bf16 v[124:127], v[100:103], v[204:207], v[124:127]
	v_mfma_f32_16x16x32_bf16 v[108:111], v[60:63], v[212:215], v[108:111]
	v_mfma_f32_16x16x32_bf16 v[104:107], v[100:103], v[212:215], v[104:107]
	v_mfma_f32_16x16x32_bf16 v[88:91], v[60:63], v[220:223], v[88:91]
	v_mfma_f32_16x16x32_bf16 v[84:87], v[100:103], v[220:223], v[84:87]
	v_mfma_f32_16x16x32_bf16 v[136:139], v[120:123], v[172:175], 0
	v_mfma_f32_16x16x32_bf16 v[132:135], v[152:155], v[172:175], 0
	v_mfma_f32_16x16x32_bf16 v[116:119], v[120:123], v[180:183], 0
	v_mfma_f32_16x16x32_bf16 v[112:115], v[152:155], v[180:183], 0
	v_mfma_f32_16x16x32_bf16 v[96:99], v[120:123], v[208:211], 0
	v_mfma_f32_16x16x32_bf16 v[92:95], v[152:155], v[208:211], 0
	v_mfma_f32_16x16x32_bf16 v[76:79], v[120:123], v[216:219], 0
	v_mfma_f32_16x16x32_bf16 v[72:75], v[152:155], v[216:219], 0
	v_mfma_f32_16x16x32_bf16 v[136:139], v[140:143], v[176:179], v[136:139]
	v_mfma_f32_16x16x32_bf16 v[132:135], v[168:171], v[176:179], v[132:135]
	v_mfma_f32_16x16x32_bf16 v[116:119], v[140:143], v[204:207], v[116:119]
	v_mfma_f32_16x16x32_bf16 v[112:115], v[168:171], v[204:207], v[112:115]
	v_mfma_f32_16x16x32_bf16 v[96:99], v[140:143], v[212:215], v[96:99]
	v_mfma_f32_16x16x32_bf16 v[92:95], v[168:171], v[212:215], v[92:95]
	v_mfma_f32_16x16x32_bf16 v[76:79], v[140:143], v[220:223], v[76:79]
	v_mfma_f32_16x16x32_bf16 v[72:75], v[168:171], v[220:223], v[72:75]
	s_barrier
	s_add_i32 s33, s69, s60
	s_mov_b32 m0, s33
	ds_read_b128 v[172:175], v202 offset:16384
	ds_read_b128 v[176:179], v202 offset:17408
	ds_read_b128 v[180:183], v202 offset:18432
	ds_read_b128 v[204:207], v202 offset:19456
	ds_read_b128 v[208:211], v202 offset:20480
	ds_read_b128 v[212:215], v202 offset:21504
	ds_read_b128 v[216:219], v202 offset:22528
	ds_read_b128 v[220:223], v202 offset:23552
	global_load_lds_dwordx4 v158, s[94:95]
	s_add_i32 m0, s33, 0x2000
	s_add_u32 s46, s94, 0x40000
	s_addc_u32 s47, s95, 0
	s_add_i32 s3, s3, s60
	global_load_lds_dwordx4 v162, s[94:95]
	s_mov_b32 m0, s3
	s_nop 0
	global_load_lds_dwordx4 v158, s[46:47]
	s_add_i32 m0, s3, 0x2000
	s_nop 0
	global_load_lds_dwordx4 v162, s[46:47]
	s_mov_b32 m0, s23
	s_nop 0
	global_load_lds_dwordx4 v156, s[96:97]
	s_mov_b32 m0, s87
	s_nop 0
	global_load_lds_dwordx4 v160, s[96:97]
	s_waitcnt vmcnt(8)
	s_waitcnt lgkmcnt(0)
	s_barrier
	v_mfma_f32_16x16x32_bf16 v[68:71], v[40:43], v[172:175], 0
	v_mfma_f32_16x16x32_bf16 v[64:67], v[80:83], v[172:175], 0
	v_mfma_f32_16x16x32_bf16 v[48:51], v[40:43], v[180:183], 0
	v_mfma_f32_16x16x32_bf16 v[44:47], v[80:83], v[180:183], 0
	v_mfma_f32_16x16x32_bf16 v[28:31], v[40:43], v[208:211], 0
	v_mfma_f32_16x16x32_bf16 v[24:27], v[80:83], v[208:211], 0
	v_mfma_f32_16x16x32_bf16 v[12:15], v[40:43], v[216:219], 0
	v_mfma_f32_16x16x32_bf16 v[8:11], v[80:83], v[216:219], 0
	v_mfma_f32_16x16x32_bf16 v[68:71], v[60:63], v[176:179], v[68:71]
	v_mfma_f32_16x16x32_bf16 v[64:67], v[100:103], v[176:179], v[64:67]
	v_mfma_f32_16x16x32_bf16 v[48:51], v[60:63], v[204:207], v[48:51]
	v_mfma_f32_16x16x32_bf16 v[44:47], v[100:103], v[204:207], v[44:47]
	v_mfma_f32_16x16x32_bf16 v[28:31], v[60:63], v[212:215], v[28:31]
	v_mfma_f32_16x16x32_bf16 v[24:27], v[100:103], v[212:215], v[24:27]
	v_mfma_f32_16x16x32_bf16 v[12:15], v[60:63], v[220:223], v[12:15]
	v_mfma_f32_16x16x32_bf16 v[8:11], v[100:103], v[220:223], v[8:11]
	v_mfma_f32_16x16x32_bf16 v[52:55], v[152:155], v[172:175], 0
	v_mfma_f32_16x16x32_bf16 v[36:39], v[120:123], v[180:183], 0
	v_mfma_f32_16x16x32_bf16 v[32:35], v[152:155], v[180:183], 0
	v_mfma_f32_16x16x32_bf16 v[20:23], v[120:123], v[208:211], 0
	v_mfma_f32_16x16x32_bf16 v[16:19], v[152:155], v[208:211], 0
	v_mfma_f32_16x16x32_bf16 v[4:7], v[120:123], v[216:219], 0
	v_mfma_f32_16x16x32_bf16 v[0:3], v[152:155], v[216:219], 0
	v_mfma_f32_16x16x32_bf16 v[40:43], v[120:123], v[172:175], 0
	v_mfma_f32_16x16x32_bf16 v[52:55], v[168:171], v[176:179], v[52:55]
	v_mfma_f32_16x16x32_bf16 v[36:39], v[140:143], v[204:207], v[36:39]
	v_mfma_f32_16x16x32_bf16 v[32:35], v[168:171], v[204:207], v[32:35]
	v_mfma_f32_16x16x32_bf16 v[20:23], v[140:143], v[212:215], v[20:23]
	v_mfma_f32_16x16x32_bf16 v[16:19], v[168:171], v[212:215], v[16:19]
	v_mfma_f32_16x16x32_bf16 v[4:7], v[140:143], v[220:223], v[4:7]
	v_mfma_f32_16x16x32_bf16 v[0:3], v[168:171], v[220:223], v[0:3]
	v_mfma_f32_16x16x32_bf16 v[40:43], v[140:143], v[176:179], v[40:43]
	s_barrier
	s_add_i32 s3, 0, 0x18000
	s_add_i32 s33, 0, 0x1c000
	ds_read_b128 v[56:59], v224 offset:32768
	ds_read_b128 v[60:63], v224 offset:33792
	ds_read_b128 v[80:83], v224 offset:34816
	ds_read_b128 v[100:103], v224 offset:35840
	ds_read_b128 v[120:123], v224 offset:49152
	ds_read_b128 v[140:143], v224 offset:50176
	ds_read_b128 v[152:155], v224 offset:51200
	ds_read_b128 v[168:171], v224 offset:52224
	s_add_u32 s46, s96, 0x40000
	s_addc_u32 s47, s97, 0
	s_mov_b32 m0, s89
	ds_read_b128 v[172:175], v202 offset:32768
	ds_read_b128 v[176:179], v202 offset:33792
	ds_read_b128 v[180:183], v202 offset:34816
	ds_read_b128 v[204:207], v202 offset:35840
	ds_read_b128 v[208:211], v202 offset:36864
	ds_read_b128 v[212:215], v202 offset:37888
	ds_read_b128 v[216:219], v202 offset:38912
	ds_read_b128 v[220:223], v202 offset:39936
	global_load_lds_dwordx4 v156, s[46:47]
	s_mov_b32 m0, s98
	s_nop 0
	global_load_lds_dwordx4 v160, s[46:47]
	s_waitcnt vmcnt(8)
	s_waitcnt lgkmcnt(0)
	s_barrier
	v_mfma_f32_16x16x32_bf16 v[148:151], v[56:59], v[172:175], v[148:151]
	v_mfma_f32_16x16x32_bf16 v[144:147], v[80:83], v[172:175], v[144:147]
	v_mfma_f32_16x16x32_bf16 v[128:131], v[56:59], v[180:183], v[128:131]
	v_mfma_f32_16x16x32_bf16 v[124:127], v[80:83], v[180:183], v[124:127]
	v_mfma_f32_16x16x32_bf16 v[108:111], v[56:59], v[208:211], v[108:111]
	v_mfma_f32_16x16x32_bf16 v[104:107], v[80:83], v[208:211], v[104:107]
	v_mfma_f32_16x16x32_bf16 v[88:91], v[56:59], v[216:219], v[88:91]
	v_mfma_f32_16x16x32_bf16 v[84:87], v[80:83], v[216:219], v[84:87]
	v_mfma_f32_16x16x32_bf16 v[148:151], v[60:63], v[176:179], v[148:151]
	v_mfma_f32_16x16x32_bf16 v[144:147], v[100:103], v[176:179], v[144:147]
	v_mfma_f32_16x16x32_bf16 v[128:131], v[60:63], v[204:207], v[128:131]
	v_mfma_f32_16x16x32_bf16 v[124:127], v[100:103], v[204:207], v[124:127]
	v_mfma_f32_16x16x32_bf16 v[108:111], v[60:63], v[212:215], v[108:111]
	v_mfma_f32_16x16x32_bf16 v[104:107], v[100:103], v[212:215], v[104:107]
	v_mfma_f32_16x16x32_bf16 v[88:91], v[60:63], v[220:223], v[88:91]
	v_mfma_f32_16x16x32_bf16 v[84:87], v[100:103], v[220:223], v[84:87]
	v_mfma_f32_16x16x32_bf16 v[136:139], v[120:123], v[172:175], v[136:139]
	v_mfma_f32_16x16x32_bf16 v[132:135], v[152:155], v[172:175], v[132:135]
	v_mfma_f32_16x16x32_bf16 v[116:119], v[120:123], v[180:183], v[116:119]
	v_mfma_f32_16x16x32_bf16 v[112:115], v[152:155], v[180:183], v[112:115]
	v_mfma_f32_16x16x32_bf16 v[96:99], v[120:123], v[208:211], v[96:99]
	v_mfma_f32_16x16x32_bf16 v[92:95], v[152:155], v[208:211], v[92:95]
	v_mfma_f32_16x16x32_bf16 v[76:79], v[120:123], v[216:219], v[76:79]
	v_mfma_f32_16x16x32_bf16 v[72:75], v[152:155], v[216:219], v[72:75]
	v_mfma_f32_16x16x32_bf16 v[136:139], v[140:143], v[176:179], v[136:139]
	v_mfma_f32_16x16x32_bf16 v[132:135], v[168:171], v[176:179], v[132:135]
	v_mfma_f32_16x16x32_bf16 v[116:119], v[140:143], v[204:207], v[116:119]
	v_mfma_f32_16x16x32_bf16 v[112:115], v[168:171], v[204:207], v[112:115]
	v_mfma_f32_16x16x32_bf16 v[96:99], v[140:143], v[212:215], v[96:99]
	v_mfma_f32_16x16x32_bf16 v[92:95], v[168:171], v[212:215], v[92:95]
	v_mfma_f32_16x16x32_bf16 v[76:79], v[140:143], v[220:223], v[76:79]
	v_mfma_f32_16x16x32_bf16 v[72:75], v[168:171], v[220:223], v[72:75]
	s_barrier
	s_add_i32 s3, s3, s60
	s_add_u32 s100, s94, 0x80
	s_addc_u32 s101, s95, 0
	s_mov_b32 m0, s3
	ds_read_b128 v[172:175], v202 offset:49152
	ds_read_b128 v[176:179], v202 offset:50176
	ds_read_b128 v[180:183], v202 offset:51200
	ds_read_b128 v[204:207], v202 offset:52224
	ds_read_b128 v[208:211], v202 offset:53248
	ds_read_b128 v[212:215], v202 offset:54272
	ds_read_b128 v[216:219], v202 offset:55296
	ds_read_b128 v[220:223], v202 offset:56320
	global_load_lds_dwordx4 v158, s[100:101]
	s_add_i32 m0, s3, 0x2000
	s_add_u32 s46, s94, 0x40080
	s_addc_u32 s47, s95, 0
	s_add_i32 s3, s33, s60
	global_load_lds_dwordx4 v162, s[100:101]
	s_mov_b32 m0, s3
	s_nop 0
	global_load_lds_dwordx4 v158, s[46:47]
	s_add_i32 m0, s3, 0x2000
	s_nop 0
	global_load_lds_dwordx4 v162, s[46:47]
	s_add_u32 s100, s96, 0x80
	s_addc_u32 s101, s97, 0
	s_mov_b32 m0, s99
	s_nop 0
	global_load_lds_dwordx4 v156, s[100:101]
	s_mov_b32 m0, s16
	s_nop 0
	global_load_lds_dwordx4 v160, s[100:101]
	s_waitcnt vmcnt(8)
	s_waitcnt lgkmcnt(0)
	s_barrier
	v_mfma_f32_16x16x32_bf16 v[68:71], v[56:59], v[172:175], v[68:71]
	v_mfma_f32_16x16x32_bf16 v[64:67], v[80:83], v[172:175], v[64:67]
	v_mfma_f32_16x16x32_bf16 v[48:51], v[56:59], v[180:183], v[48:51]
	v_mfma_f32_16x16x32_bf16 v[44:47], v[80:83], v[180:183], v[44:47]
	v_mfma_f32_16x16x32_bf16 v[28:31], v[56:59], v[208:211], v[28:31]
	v_mfma_f32_16x16x32_bf16 v[24:27], v[80:83], v[208:211], v[24:27]
	v_mfma_f32_16x16x32_bf16 v[12:15], v[56:59], v[216:219], v[12:15]
	v_mfma_f32_16x16x32_bf16 v[8:11], v[80:83], v[216:219], v[8:11]
	v_mfma_f32_16x16x32_bf16 v[68:71], v[60:63], v[176:179], v[68:71]
	v_mfma_f32_16x16x32_bf16 v[64:67], v[100:103], v[176:179], v[64:67]
	v_mfma_f32_16x16x32_bf16 v[48:51], v[60:63], v[204:207], v[48:51]
	v_mfma_f32_16x16x32_bf16 v[44:47], v[100:103], v[204:207], v[44:47]
	v_mfma_f32_16x16x32_bf16 v[28:31], v[60:63], v[212:215], v[28:31]
	v_mfma_f32_16x16x32_bf16 v[24:27], v[100:103], v[212:215], v[24:27]
	v_mfma_f32_16x16x32_bf16 v[12:15], v[60:63], v[220:223], v[12:15]
	v_mfma_f32_16x16x32_bf16 v[8:11], v[100:103], v[220:223], v[8:11]
	v_mfma_f32_16x16x32_bf16 v[40:43], v[120:123], v[172:175], v[40:43]
	v_mfma_f32_16x16x32_bf16 v[56:59], v[140:143], v[176:179], v[40:43]
	v_mfma_f32_16x16x32_bf16 v[40:43], v[152:155], v[172:175], v[52:55]
	v_mfma_f32_16x16x32_bf16 v[36:39], v[120:123], v[180:183], v[36:39]
	v_mfma_f32_16x16x32_bf16 v[32:35], v[152:155], v[180:183], v[32:35]
	v_mfma_f32_16x16x32_bf16 v[20:23], v[120:123], v[208:211], v[20:23]
	v_mfma_f32_16x16x32_bf16 v[16:19], v[152:155], v[208:211], v[16:19]
	v_mfma_f32_16x16x32_bf16 v[4:7], v[120:123], v[216:219], v[4:7]
	v_mfma_f32_16x16x32_bf16 v[0:3], v[152:155], v[216:219], v[0:3]
	v_mfma_f32_16x16x32_bf16 v[52:55], v[168:171], v[176:179], v[40:43]
	v_mfma_f32_16x16x32_bf16 v[36:39], v[140:143], v[204:207], v[36:39]
	v_mfma_f32_16x16x32_bf16 v[32:35], v[168:171], v[204:207], v[32:35]
	v_mfma_f32_16x16x32_bf16 v[20:23], v[140:143], v[212:215], v[20:23]
	v_mfma_f32_16x16x32_bf16 v[16:19], v[168:171], v[212:215], v[16:19]
	v_mfma_f32_16x16x32_bf16 v[4:7], v[140:143], v[220:223], v[4:7]
	v_mfma_f32_16x16x32_bf16 v[0:3], v[168:171], v[220:223], v[0:3]
	s_barrier
	s_add_i32 s31, s31, 2
	s_cmp_gt_u32 s31, 13
	s_mov_b64 s[46:47], s[50:51]
	s_cbranch_scc1 .Lpeel_exit_mixin
.LBB0_329:
	s_add_u32 s50, s46, 0x100
	s_addc_u32 s51, s47, 0
	s_add_u32 s3, s46, 0xfffff900
	s_addc_u32 s33, s47, -1
	s_cmp_gt_u32 s50, 0x7ff
	s_cselect_b32 s50, s3, s50
	s_cselect_b32 s51, s33, s51
	s_add_u32 s3, s92, s50
	s_addc_u32 s33, s93, s51
	s_add_u32 s43, s36, s50
	s_addc_u32 s54, s37, s51
	s_add_i32 s69, 0, 0x10000
	s_cmp_eq_u32 s31, 12
	s_cselect_b32 s97, s7, s33
	s_cselect_b32 s96, s11, s3
	s_cselect_b32 s95, s0, s54
	s_cselect_b32 s94, s29, s43
	s_add_i32 s3, 0, 0x14000
	ds_read_b128 v[40:43], v224
	ds_read_b128 v[60:63], v224 offset:1024
	ds_read_b128 v[80:83], v224 offset:2048
	ds_read_b128 v[100:103], v224 offset:3072
	ds_read_b128 v[120:123], v224 offset:16384
	ds_read_b128 v[140:143], v224 offset:17408
	ds_read_b128 v[152:155], v224 offset:18432
	ds_read_b128 v[168:171], v224 offset:19456
	s_add_u32 s33, s92, s46
	s_addc_u32 s43, s93, s47
	s_add_u32 s46, s33, 0x40080
	s_addc_u32 s47, s43, 0
	s_add_i32 m0, s23, 0xc000
	ds_read_b128 v[172:175], v202
	ds_read_b128 v[176:179], v202 offset:1024
	ds_read_b128 v[180:183], v202 offset:2048
	ds_read_b128 v[204:207], v202 offset:3072
	ds_read_b128 v[208:211], v202 offset:4096
	ds_read_b128 v[212:215], v202 offset:5120
	ds_read_b128 v[216:219], v202 offset:6144
	ds_read_b128 v[220:223], v202 offset:7168
	global_load_lds_dwordx4 v156, s[46:47]
	s_add_i32 m0, s23, 0xe000
	s_nop 0
	global_load_lds_dwordx4 v160, s[46:47]
	s_waitcnt vmcnt(8)
	s_waitcnt lgkmcnt(0)
	s_barrier
	v_mfma_f32_16x16x32_bf16 v[148:151], v[40:43], v[172:175], v[148:151]
	v_mfma_f32_16x16x32_bf16 v[144:147], v[80:83], v[172:175], v[144:147]
	v_mfma_f32_16x16x32_bf16 v[128:131], v[40:43], v[180:183], v[128:131]
	v_mfma_f32_16x16x32_bf16 v[124:127], v[80:83], v[180:183], v[124:127]
	v_mfma_f32_16x16x32_bf16 v[108:111], v[40:43], v[208:211], v[108:111]
	v_mfma_f32_16x16x32_bf16 v[104:107], v[80:83], v[208:211], v[104:107]
	v_mfma_f32_16x16x32_bf16 v[88:91], v[40:43], v[216:219], v[88:91]
	v_mfma_f32_16x16x32_bf16 v[84:87], v[80:83], v[216:219], v[84:87]
	v_mfma_f32_16x16x32_bf16 v[148:151], v[60:63], v[176:179], v[148:151]
	v_mfma_f32_16x16x32_bf16 v[144:147], v[100:103], v[176:179], v[144:147]
	v_mfma_f32_16x16x32_bf16 v[128:131], v[60:63], v[204:207], v[128:131]
	v_mfma_f32_16x16x32_bf16 v[124:127], v[100:103], v[204:207], v[124:127]
	v_mfma_f32_16x16x32_bf16 v[108:111], v[60:63], v[212:215], v[108:111]
	v_mfma_f32_16x16x32_bf16 v[104:107], v[100:103], v[212:215], v[104:107]
	v_mfma_f32_16x16x32_bf16 v[88:91], v[60:63], v[220:223], v[88:91]
	v_mfma_f32_16x16x32_bf16 v[84:87], v[100:103], v[220:223], v[84:87]
	v_mfma_f32_16x16x32_bf16 v[136:139], v[120:123], v[172:175], v[136:139]
	v_mfma_f32_16x16x32_bf16 v[132:135], v[152:155], v[172:175], v[132:135]
	v_mfma_f32_16x16x32_bf16 v[116:119], v[120:123], v[180:183], v[116:119]
	v_mfma_f32_16x16x32_bf16 v[112:115], v[152:155], v[180:183], v[112:115]
	v_mfma_f32_16x16x32_bf16 v[96:99], v[120:123], v[208:211], v[96:99]
	v_mfma_f32_16x16x32_bf16 v[92:95], v[152:155], v[208:211], v[92:95]
	v_mfma_f32_16x16x32_bf16 v[76:79], v[120:123], v[216:219], v[76:79]
	v_mfma_f32_16x16x32_bf16 v[72:75], v[152:155], v[216:219], v[72:75]
	v_mfma_f32_16x16x32_bf16 v[136:139], v[140:143], v[176:179], v[136:139]
	v_mfma_f32_16x16x32_bf16 v[132:135], v[168:171], v[176:179], v[132:135]
	v_mfma_f32_16x16x32_bf16 v[116:119], v[140:143], v[204:207], v[116:119]
	v_mfma_f32_16x16x32_bf16 v[112:115], v[168:171], v[204:207], v[112:115]
	v_mfma_f32_16x16x32_bf16 v[96:99], v[140:143], v[212:215], v[96:99]
	v_mfma_f32_16x16x32_bf16 v[92:95], v[168:171], v[212:215], v[92:95]
	v_mfma_f32_16x16x32_bf16 v[76:79], v[140:143], v[220:223], v[76:79]
	v_mfma_f32_16x16x32_bf16 v[72:75], v[168:171], v[220:223], v[72:75]
	s_barrier
	s_add_i32 s33, s69, s60
	s_mov_b32 m0, s33
	ds_read_b128 v[172:175], v202 offset:16384
	ds_read_b128 v[176:179], v202 offset:17408
	ds_read_b128 v[180:183], v202 offset:18432
	ds_read_b128 v[204:207], v202 offset:19456
	ds_read_b128 v[208:211], v202 offset:20480
	ds_read_b128 v[212:215], v202 offset:21504
	ds_read_b128 v[216:219], v202 offset:22528
	ds_read_b128 v[220:223], v202 offset:23552
	global_load_lds_dwordx4 v158, s[94:95]
	s_add_i32 m0, s33, 0x2000
	s_add_u32 s46, s94, 0x40000
	s_addc_u32 s47, s95, 0
	s_add_i32 s3, s3, s60
	global_load_lds_dwordx4 v162, s[94:95]
	s_mov_b32 m0, s3
	s_nop 0
	global_load_lds_dwordx4 v158, s[46:47]
	s_add_i32 m0, s3, 0x2000
	s_nop 0
	global_load_lds_dwordx4 v162, s[46:47]
	s_mov_b32 m0, s23
	s_nop 0
	global_load_lds_dwordx4 v156, s[96:97]
	s_mov_b32 m0, s87
	s_nop 0
	global_load_lds_dwordx4 v160, s[96:97]
	s_waitcnt vmcnt(8)
	s_waitcnt lgkmcnt(0)
	s_barrier
	v_mfma_f32_16x16x32_bf16 v[68:71], v[40:43], v[172:175], v[68:71]
	v_mfma_f32_16x16x32_bf16 v[64:67], v[80:83], v[172:175], v[64:67]
	v_mfma_f32_16x16x32_bf16 v[48:51], v[40:43], v[180:183], v[48:51]
	v_mfma_f32_16x16x32_bf16 v[44:47], v[80:83], v[180:183], v[44:47]
	v_mfma_f32_16x16x32_bf16 v[28:31], v[40:43], v[208:211], v[28:31]
	v_mfma_f32_16x16x32_bf16 v[24:27], v[80:83], v[208:211], v[24:27]
	v_mfma_f32_16x16x32_bf16 v[12:15], v[40:43], v[216:219], v[12:15]
	v_mfma_f32_16x16x32_bf16 v[8:11], v[80:83], v[216:219], v[8:11]
	v_mfma_f32_16x16x32_bf16 v[68:71], v[60:63], v[176:179], v[68:71]
	v_mfma_f32_16x16x32_bf16 v[64:67], v[100:103], v[176:179], v[64:67]
	v_mfma_f32_16x16x32_bf16 v[48:51], v[60:63], v[204:207], v[48:51]
	v_mfma_f32_16x16x32_bf16 v[44:47], v[100:103], v[204:207], v[44:47]
	v_mfma_f32_16x16x32_bf16 v[28:31], v[60:63], v[212:215], v[28:31]
	v_mfma_f32_16x16x32_bf16 v[24:27], v[100:103], v[212:215], v[24:27]
	v_mfma_f32_16x16x32_bf16 v[12:15], v[60:63], v[220:223], v[12:15]
	v_mfma_f32_16x16x32_bf16 v[8:11], v[100:103], v[220:223], v[8:11]
	v_mfma_f32_16x16x32_bf16 v[52:55], v[152:155], v[172:175], v[52:55]
	v_mfma_f32_16x16x32_bf16 v[36:39], v[120:123], v[180:183], v[36:39]
	v_mfma_f32_16x16x32_bf16 v[32:35], v[152:155], v[180:183], v[32:35]
	v_mfma_f32_16x16x32_bf16 v[20:23], v[120:123], v[208:211], v[20:23]
	v_mfma_f32_16x16x32_bf16 v[16:19], v[152:155], v[208:211], v[16:19]
	v_mfma_f32_16x16x32_bf16 v[4:7], v[120:123], v[216:219], v[4:7]
	v_mfma_f32_16x16x32_bf16 v[0:3], v[152:155], v[216:219], v[0:3]
	v_mfma_f32_16x16x32_bf16 v[40:43], v[120:123], v[172:175], v[56:59]
	v_mfma_f32_16x16x32_bf16 v[52:55], v[168:171], v[176:179], v[52:55]
	v_mfma_f32_16x16x32_bf16 v[36:39], v[140:143], v[204:207], v[36:39]
	v_mfma_f32_16x16x32_bf16 v[32:35], v[168:171], v[204:207], v[32:35]
	v_mfma_f32_16x16x32_bf16 v[20:23], v[140:143], v[212:215], v[20:23]
	v_mfma_f32_16x16x32_bf16 v[16:19], v[168:171], v[212:215], v[16:19]
	v_mfma_f32_16x16x32_bf16 v[4:7], v[140:143], v[220:223], v[4:7]
	v_mfma_f32_16x16x32_bf16 v[0:3], v[168:171], v[220:223], v[0:3]
	v_mfma_f32_16x16x32_bf16 v[40:43], v[140:143], v[176:179], v[40:43]
	s_barrier
	s_add_i32 s3, 0, 0x18000
	s_add_i32 s33, 0, 0x1c000
	ds_read_b128 v[56:59], v224 offset:32768
	ds_read_b128 v[60:63], v224 offset:33792
	ds_read_b128 v[80:83], v224 offset:34816
	ds_read_b128 v[100:103], v224 offset:35840
	ds_read_b128 v[120:123], v224 offset:49152
	ds_read_b128 v[140:143], v224 offset:50176
	ds_read_b128 v[152:155], v224 offset:51200
	ds_read_b128 v[168:171], v224 offset:52224
	s_add_u32 s46, s96, 0x40000
	s_addc_u32 s47, s97, 0
	s_mov_b32 m0, s89
	ds_read_b128 v[172:175], v202 offset:32768
	ds_read_b128 v[176:179], v202 offset:33792
	ds_read_b128 v[180:183], v202 offset:34816
	ds_read_b128 v[204:207], v202 offset:35840
	ds_read_b128 v[208:211], v202 offset:36864
	ds_read_b128 v[212:215], v202 offset:37888
	ds_read_b128 v[216:219], v202 offset:38912
	ds_read_b128 v[220:223], v202 offset:39936
	global_load_lds_dwordx4 v156, s[46:47]
	s_mov_b32 m0, s98
	s_nop 0
	global_load_lds_dwordx4 v160, s[46:47]
	s_waitcnt vmcnt(8)
	s_waitcnt lgkmcnt(0)
	s_barrier
	v_mfma_f32_16x16x32_bf16 v[148:151], v[56:59], v[172:175], v[148:151]
	v_mfma_f32_16x16x32_bf16 v[144:147], v[80:83], v[172:175], v[144:147]
	v_mfma_f32_16x16x32_bf16 v[128:131], v[56:59], v[180:183], v[128:131]
	v_mfma_f32_16x16x32_bf16 v[124:127], v[80:83], v[180:183], v[124:127]
	v_mfma_f32_16x16x32_bf16 v[108:111], v[56:59], v[208:211], v[108:111]
	v_mfma_f32_16x16x32_bf16 v[104:107], v[80:83], v[208:211], v[104:107]
	v_mfma_f32_16x16x32_bf16 v[88:91], v[56:59], v[216:219], v[88:91]
	v_mfma_f32_16x16x32_bf16 v[84:87], v[80:83], v[216:219], v[84:87]
	v_mfma_f32_16x16x32_bf16 v[148:151], v[60:63], v[176:179], v[148:151]
	v_mfma_f32_16x16x32_bf16 v[144:147], v[100:103], v[176:179], v[144:147]
	v_mfma_f32_16x16x32_bf16 v[128:131], v[60:63], v[204:207], v[128:131]
	v_mfma_f32_16x16x32_bf16 v[124:127], v[100:103], v[204:207], v[124:127]
	v_mfma_f32_16x16x32_bf16 v[108:111], v[60:63], v[212:215], v[108:111]
	v_mfma_f32_16x16x32_bf16 v[104:107], v[100:103], v[212:215], v[104:107]
	v_mfma_f32_16x16x32_bf16 v[88:91], v[60:63], v[220:223], v[88:91]
	v_mfma_f32_16x16x32_bf16 v[84:87], v[100:103], v[220:223], v[84:87]
	v_mfma_f32_16x16x32_bf16 v[136:139], v[120:123], v[172:175], v[136:139]
	v_mfma_f32_16x16x32_bf16 v[132:135], v[152:155], v[172:175], v[132:135]
	v_mfma_f32_16x16x32_bf16 v[116:119], v[120:123], v[180:183], v[116:119]
	v_mfma_f32_16x16x32_bf16 v[112:115], v[152:155], v[180:183], v[112:115]
	v_mfma_f32_16x16x32_bf16 v[96:99], v[120:123], v[208:211], v[96:99]
	v_mfma_f32_16x16x32_bf16 v[92:95], v[152:155], v[208:211], v[92:95]
	v_mfma_f32_16x16x32_bf16 v[76:79], v[120:123], v[216:219], v[76:79]
	v_mfma_f32_16x16x32_bf16 v[72:75], v[152:155], v[216:219], v[72:75]
	v_mfma_f32_16x16x32_bf16 v[136:139], v[140:143], v[176:179], v[136:139]
	v_mfma_f32_16x16x32_bf16 v[132:135], v[168:171], v[176:179], v[132:135]
	v_mfma_f32_16x16x32_bf16 v[116:119], v[140:143], v[204:207], v[116:119]
	v_mfma_f32_16x16x32_bf16 v[112:115], v[168:171], v[204:207], v[112:115]
	v_mfma_f32_16x16x32_bf16 v[96:99], v[140:143], v[212:215], v[96:99]
	v_mfma_f32_16x16x32_bf16 v[92:95], v[168:171], v[212:215], v[92:95]
	v_mfma_f32_16x16x32_bf16 v[76:79], v[140:143], v[220:223], v[76:79]
	v_mfma_f32_16x16x32_bf16 v[72:75], v[168:171], v[220:223], v[72:75]
	s_barrier
	s_add_i32 s3, s3, s60
	s_add_u32 s100, s94, 0x80
	s_addc_u32 s101, s95, 0
	s_mov_b32 m0, s3
	ds_read_b128 v[172:175], v202 offset:49152
	ds_read_b128 v[176:179], v202 offset:50176
	ds_read_b128 v[180:183], v202 offset:51200
	ds_read_b128 v[204:207], v202 offset:52224
	ds_read_b128 v[208:211], v202 offset:53248
	ds_read_b128 v[212:215], v202 offset:54272
	ds_read_b128 v[216:219], v202 offset:55296
	ds_read_b128 v[220:223], v202 offset:56320
	global_load_lds_dwordx4 v158, s[100:101]
	s_add_i32 m0, s3, 0x2000
	s_add_u32 s46, s94, 0x40080
	s_addc_u32 s47, s95, 0
	s_add_i32 s3, s33, s60
	global_load_lds_dwordx4 v162, s[100:101]
	s_mov_b32 m0, s3
	s_nop 0
	global_load_lds_dwordx4 v158, s[46:47]
	s_add_i32 m0, s3, 0x2000
	s_nop 0
	global_load_lds_dwordx4 v162, s[46:47]
	s_add_u32 s100, s96, 0x80
	s_addc_u32 s101, s97, 0
	s_mov_b32 m0, s99
	s_nop 0
	global_load_lds_dwordx4 v156, s[100:101]
	s_mov_b32 m0, s16
	s_nop 0
	global_load_lds_dwordx4 v160, s[100:101]
	s_waitcnt vmcnt(8)
	s_waitcnt lgkmcnt(0)
	s_barrier
	v_mfma_f32_16x16x32_bf16 v[68:71], v[56:59], v[172:175], v[68:71]
	v_mfma_f32_16x16x32_bf16 v[64:67], v[80:83], v[172:175], v[64:67]
	v_mfma_f32_16x16x32_bf16 v[48:51], v[56:59], v[180:183], v[48:51]
	v_mfma_f32_16x16x32_bf16 v[44:47], v[80:83], v[180:183], v[44:47]
	v_mfma_f32_16x16x32_bf16 v[28:31], v[56:59], v[208:211], v[28:31]
	v_mfma_f32_16x16x32_bf16 v[24:27], v[80:83], v[208:211], v[24:27]
	v_mfma_f32_16x16x32_bf16 v[12:15], v[56:59], v[216:219], v[12:15]
	v_mfma_f32_16x16x32_bf16 v[8:11], v[80:83], v[216:219], v[8:11]
	v_mfma_f32_16x16x32_bf16 v[68:71], v[60:63], v[176:179], v[68:71]
	v_mfma_f32_16x16x32_bf16 v[64:67], v[100:103], v[176:179], v[64:67]
	v_mfma_f32_16x16x32_bf16 v[48:51], v[60:63], v[204:207], v[48:51]
	v_mfma_f32_16x16x32_bf16 v[44:47], v[100:103], v[204:207], v[44:47]
	v_mfma_f32_16x16x32_bf16 v[28:31], v[60:63], v[212:215], v[28:31]
	v_mfma_f32_16x16x32_bf16 v[24:27], v[100:103], v[212:215], v[24:27]
	v_mfma_f32_16x16x32_bf16 v[12:15], v[60:63], v[220:223], v[12:15]
	v_mfma_f32_16x16x32_bf16 v[8:11], v[100:103], v[220:223], v[8:11]
	v_mfma_f32_16x16x32_bf16 v[40:43], v[120:123], v[172:175], v[40:43]
	v_mfma_f32_16x16x32_bf16 v[56:59], v[140:143], v[176:179], v[40:43]
	v_mfma_f32_16x16x32_bf16 v[40:43], v[152:155], v[172:175], v[52:55]
	v_mfma_f32_16x16x32_bf16 v[36:39], v[120:123], v[180:183], v[36:39]
	v_mfma_f32_16x16x32_bf16 v[32:35], v[152:155], v[180:183], v[32:35]
	v_mfma_f32_16x16x32_bf16 v[20:23], v[120:123], v[208:211], v[20:23]
	v_mfma_f32_16x16x32_bf16 v[16:19], v[152:155], v[208:211], v[16:19]
	v_mfma_f32_16x16x32_bf16 v[4:7], v[120:123], v[216:219], v[4:7]
	v_mfma_f32_16x16x32_bf16 v[0:3], v[152:155], v[216:219], v[0:3]
	v_mfma_f32_16x16x32_bf16 v[52:55], v[168:171], v[176:179], v[40:43]
	v_mfma_f32_16x16x32_bf16 v[36:39], v[140:143], v[204:207], v[36:39]
	v_mfma_f32_16x16x32_bf16 v[32:35], v[168:171], v[204:207], v[32:35]
	v_mfma_f32_16x16x32_bf16 v[20:23], v[140:143], v[212:215], v[20:23]
	v_mfma_f32_16x16x32_bf16 v[16:19], v[168:171], v[212:215], v[16:19]
	v_mfma_f32_16x16x32_bf16 v[4:7], v[140:143], v[220:223], v[4:7]
	v_mfma_f32_16x16x32_bf16 v[0:3], v[168:171], v[220:223], v[0:3]
	s_barrier
	s_add_i32 s31, s31, 2
	s_cmp_gt_u32 s31, 13
	s_mov_b64 s[46:47], s[50:51]
	s_cbranch_scc0 .LBB0_329

.Lprio_re:
	s_add_u32 s38, s36, 0x100
	s_addc_u32 s39, s37, 0
	s_cmp_ge_u32 s38, s24
	s_cselect_b32 s47, s24, 0
	s_cselect_b32 s46, 0, 0
	s_sub_u32 s38, s38, s47
	s_subb_u32 s39, s39, s46
	s_sub_u32 s47, s36, s47
	s_subb_u32 s46, s37, s46
	s_add_u32 vcc_lo, s34, s47
	s_addc_u32 vcc_hi, s35, s46
	s_add_u32 vcc_lo, vcc_lo, 0x100
	s_addc_u32 vcc_hi, vcc_hi, 0
	s_add_u32 s47, s30, s47
	s_addc_u32 s46, s31, s46
	s_add_u32 s69, s47, 0x100
	s_addc_u32 s3, s46, 0
	s_add_i32 s33, 0, 0x10000
	s_cmp_eq_u32 s99, s86
	s_cselect_b32 s47, s11, vcc_hi
	s_cselect_b32 s46, s10, vcc_lo
	s_cselect_b32 vcc_hi, s29, s3
	s_cselect_b32 vcc_lo, s28, s69
	s_add_i32 s3, 0, 0x14000
	ds_read_b128 v[120:123], v212
	ds_read_b128 v[124:127], v212 offset:1024
	ds_read_b128 v[128:131], v212 offset:2048
	ds_read_b128 v[132:135], v212 offset:3072
	ds_read_b128 v[136:139], v212 offset:16384
	ds_read_b128 v[140:143], v212 offset:17408
	ds_read_b128 v[144:147], v212 offset:18432
	ds_read_b128 v[148:151], v212 offset:19456
	s_add_u32 s36, s0, s36
	s_addc_u32 s37, s43, s37
	s_add_u32 s100, s36, 0x80
	s_addc_u32 s101, s37, 0
	s_add_i32 m0, s94, 0xc000
	ds_read_b128 v[152:155], v248
	ds_read_b128 v[156:159], v248 offset:1024
	ds_read_b128 v[160:163], v248 offset:2048
	ds_read_b128 v[172:175], v248 offset:3072
	ds_read_b128 v[176:179], v248 offset:4096
	ds_read_b128 v[180:183], v248 offset:5120
	ds_read_b128 v[184:187], v248 offset:6144
	ds_read_b128 v[208:211], v248 offset:7168
	global_load_lds_dwordx4 v202, s[100:101]
	s_add_i32 m0, s94, 0xe000
	s_nop 0
	global_load_lds_dwordx4 v204, s[100:101]
	s_waitcnt vmcnt(8)
	s_waitcnt lgkmcnt(0)
	s_barrier
	v_mfma_f32_16x16x32_bf16 v[168:171], v[120:123], v[152:155], 0
	v_mfma_f32_16x16x32_bf16 v[164:167], v[128:131], v[152:155], 0
	v_mfma_f32_16x16x32_bf16 v[108:111], v[120:123], v[160:163], 0
	v_mfma_f32_16x16x32_bf16 v[104:107], v[128:131], v[160:163], 0
	v_mfma_f32_16x16x32_bf16 v[92:95], v[120:123], v[176:179], 0
	v_mfma_f32_16x16x32_bf16 v[88:91], v[128:131], v[176:179], 0
	v_mfma_f32_16x16x32_bf16 v[76:79], v[120:123], v[184:187], 0
	v_mfma_f32_16x16x32_bf16 v[72:75], v[128:131], v[184:187], 0
	v_mfma_f32_16x16x32_bf16 v[168:171], v[124:127], v[156:159], v[168:171]
	v_mfma_f32_16x16x32_bf16 v[164:167], v[132:135], v[156:159], v[164:167]
	v_mfma_f32_16x16x32_bf16 v[108:111], v[124:127], v[172:175], v[108:111]
	v_mfma_f32_16x16x32_bf16 v[104:107], v[132:135], v[172:175], v[104:107]
	v_mfma_f32_16x16x32_bf16 v[92:95], v[124:127], v[180:183], v[92:95]
	v_mfma_f32_16x16x32_bf16 v[88:91], v[132:135], v[180:183], v[88:91]
	v_mfma_f32_16x16x32_bf16 v[76:79], v[124:127], v[208:211], v[76:79]
	v_mfma_f32_16x16x32_bf16 v[72:75], v[132:135], v[208:211], v[72:75]
	v_mfma_f32_16x16x32_bf16 v[116:119], v[136:139], v[152:155], 0
	v_mfma_f32_16x16x32_bf16 v[112:115], v[144:147], v[152:155], 0
	v_mfma_f32_16x16x32_bf16 v[100:103], v[136:139], v[160:163], 0
	v_mfma_f32_16x16x32_bf16 v[96:99], v[144:147], v[160:163], 0
	v_mfma_f32_16x16x32_bf16 v[84:87], v[136:139], v[176:179], 0
	v_mfma_f32_16x16x32_bf16 v[80:83], v[144:147], v[176:179], 0
	v_mfma_f32_16x16x32_bf16 v[68:71], v[136:139], v[184:187], 0
	v_mfma_f32_16x16x32_bf16 v[64:67], v[144:147], v[184:187], 0
	v_mfma_f32_16x16x32_bf16 v[116:119], v[140:143], v[156:159], v[116:119]
	v_mfma_f32_16x16x32_bf16 v[112:115], v[148:151], v[156:159], v[112:115]
	v_mfma_f32_16x16x32_bf16 v[100:103], v[140:143], v[172:175], v[100:103]
	v_mfma_f32_16x16x32_bf16 v[96:99], v[148:151], v[172:175], v[96:99]
	v_mfma_f32_16x16x32_bf16 v[84:87], v[140:143], v[180:183], v[84:87]
	v_mfma_f32_16x16x32_bf16 v[80:83], v[148:151], v[180:183], v[80:83]
	v_mfma_f32_16x16x32_bf16 v[68:71], v[140:143], v[208:211], v[68:71]
	v_mfma_f32_16x16x32_bf16 v[64:67], v[148:151], v[208:211], v[64:67]
	s_barrier
	s_add_i32 s33, s33, s89
	s_mov_b64 s[100:101], vcc
	s_mov_b32 m0, s33
	ds_read_b128 v[152:155], v248 offset:16384
	ds_read_b128 v[156:159], v248 offset:17408
	ds_read_b128 v[160:163], v248 offset:18432
	ds_read_b128 v[172:175], v248 offset:19456
	ds_read_b128 v[176:179], v248 offset:20480
	ds_read_b128 v[180:183], v248 offset:21504
	ds_read_b128 v[184:187], v248 offset:22528
	ds_read_b128 v[208:211], v248 offset:23552
	global_load_lds_dwordx4 v188, s[100:101]
	s_add_i32 m0, s33, 0x2000
	s_add_u32 s36, vcc_lo, s92
	s_addc_u32 s37, vcc_hi, 0
	s_add_i32 s3, s3, s89
	global_load_lds_dwordx4 v206, s[100:101]
	s_mov_b32 m0, s3
	s_nop 0
	global_load_lds_dwordx4 v188, s[36:37]
	s_add_i32 m0, s3, 0x2000
	s_nop 0
	global_load_lds_dwordx4 v206, s[36:37]
	s_mov_b32 m0, s94
	s_nop 0
	global_load_lds_dwordx4 v202, s[46:47]
	s_mov_b32 m0, s95
	s_nop 0
	global_load_lds_dwordx4 v204, s[46:47]
	s_waitcnt vmcnt(8)
	s_waitcnt lgkmcnt(0)
	s_barrier
	v_mfma_f32_16x16x32_bf16 v[60:63], v[120:123], v[152:155], 0
	v_mfma_f32_16x16x32_bf16 v[56:59], v[128:131], v[152:155], 0
	v_mfma_f32_16x16x32_bf16 v[44:47], v[120:123], v[160:163], 0
	v_mfma_f32_16x16x32_bf16 v[40:43], v[128:131], v[160:163], 0
	v_mfma_f32_16x16x32_bf16 v[28:31], v[120:123], v[176:179], 0
	v_mfma_f32_16x16x32_bf16 v[24:27], v[128:131], v[176:179], 0
	v_mfma_f32_16x16x32_bf16 v[12:15], v[120:123], v[184:187], 0
	v_mfma_f32_16x16x32_bf16 v[8:11], v[128:131], v[184:187], 0
	v_mfma_f32_16x16x32_bf16 v[60:63], v[124:127], v[156:159], v[60:63]
	v_mfma_f32_16x16x32_bf16 v[56:59], v[132:135], v[156:159], v[56:59]
	v_mfma_f32_16x16x32_bf16 v[44:47], v[124:127], v[172:175], v[44:47]
	v_mfma_f32_16x16x32_bf16 v[40:43], v[132:135], v[172:175], v[40:43]
	v_mfma_f32_16x16x32_bf16 v[28:31], v[124:127], v[180:183], v[28:31]
	v_mfma_f32_16x16x32_bf16 v[24:27], v[132:135], v[180:183], v[24:27]
	v_mfma_f32_16x16x32_bf16 v[12:15], v[124:127], v[208:211], v[12:15]
	v_mfma_f32_16x16x32_bf16 v[8:11], v[132:135], v[208:211], v[8:11]
	v_mfma_f32_16x16x32_bf16 v[52:55], v[136:139], v[152:155], 0
	v_mfma_f32_16x16x32_bf16 v[48:51], v[144:147], v[152:155], 0
	v_mfma_f32_16x16x32_bf16 v[36:39], v[136:139], v[160:163], 0
	v_mfma_f32_16x16x32_bf16 v[32:35], v[144:147], v[160:163], 0
	v_mfma_f32_16x16x32_bf16 v[20:23], v[136:139], v[176:179], 0
	v_mfma_f32_16x16x32_bf16 v[16:19], v[144:147], v[176:179], 0
	v_mfma_f32_16x16x32_bf16 v[4:7], v[136:139], v[184:187], 0
	v_mfma_f32_16x16x32_bf16 v[0:3], v[144:147], v[184:187], 0
	v_mfma_f32_16x16x32_bf16 v[52:55], v[140:143], v[156:159], v[52:55]
	v_mfma_f32_16x16x32_bf16 v[48:51], v[148:151], v[156:159], v[48:51]
	v_mfma_f32_16x16x32_bf16 v[36:39], v[140:143], v[172:175], v[36:39]
	v_mfma_f32_16x16x32_bf16 v[32:35], v[148:151], v[172:175], v[32:35]
	v_mfma_f32_16x16x32_bf16 v[20:23], v[140:143], v[180:183], v[20:23]
	v_mfma_f32_16x16x32_bf16 v[16:19], v[148:151], v[180:183], v[16:19]
	v_mfma_f32_16x16x32_bf16 v[4:7], v[140:143], v[208:211], v[4:7]
	v_mfma_f32_16x16x32_bf16 v[0:3], v[148:151], v[208:211], v[0:3]
	s_barrier
	s_add_i32 s3, 0, 0x18000
	s_add_i32 s33, 0, 0x1c000
	ds_read_b128 v[120:123], v212 offset:32768
	ds_read_b128 v[124:127], v212 offset:33792
	ds_read_b128 v[128:131], v212 offset:34816
	ds_read_b128 v[132:135], v212 offset:35840
	ds_read_b128 v[136:139], v212 offset:49152
	ds_read_b128 v[140:143], v212 offset:50176
	ds_read_b128 v[144:147], v212 offset:51200
	ds_read_b128 v[148:151], v212 offset:52224
	s_add_u32 s36, s46, s92
	s_addc_u32 s37, s47, 0
	s_mov_b32 m0, s96
	ds_read_b128 v[152:155], v248 offset:32768
	ds_read_b128 v[156:159], v248 offset:33792
	ds_read_b128 v[160:163], v248 offset:34816
	ds_read_b128 v[172:175], v248 offset:35840
	ds_read_b128 v[176:179], v248 offset:36864
	ds_read_b128 v[180:183], v248 offset:37888
	ds_read_b128 v[184:187], v248 offset:38912
	ds_read_b128 v[208:211], v248 offset:39936
	global_load_lds_dwordx4 v202, s[36:37]
	s_mov_b32 m0, s97
	s_nop 0
	global_load_lds_dwordx4 v204, s[36:37]
	s_waitcnt vmcnt(8)
	s_waitcnt lgkmcnt(0)
	s_barrier
	v_mfma_f32_16x16x32_bf16 v[168:171], v[120:123], v[152:155], v[168:171]
	v_mfma_f32_16x16x32_bf16 v[164:167], v[128:131], v[152:155], v[164:167]
	v_mfma_f32_16x16x32_bf16 v[108:111], v[120:123], v[160:163], v[108:111]
	v_mfma_f32_16x16x32_bf16 v[104:107], v[128:131], v[160:163], v[104:107]
	v_mfma_f32_16x16x32_bf16 v[92:95], v[120:123], v[176:179], v[92:95]
	v_mfma_f32_16x16x32_bf16 v[88:91], v[128:131], v[176:179], v[88:91]
	v_mfma_f32_16x16x32_bf16 v[76:79], v[120:123], v[184:187], v[76:79]
	v_mfma_f32_16x16x32_bf16 v[72:75], v[128:131], v[184:187], v[72:75]
	v_mfma_f32_16x16x32_bf16 v[168:171], v[124:127], v[156:159], v[168:171]
	v_mfma_f32_16x16x32_bf16 v[164:167], v[132:135], v[156:159], v[164:167]
	v_mfma_f32_16x16x32_bf16 v[108:111], v[124:127], v[172:175], v[108:111]
	v_mfma_f32_16x16x32_bf16 v[104:107], v[132:135], v[172:175], v[104:107]
	v_mfma_f32_16x16x32_bf16 v[92:95], v[124:127], v[180:183], v[92:95]
	v_mfma_f32_16x16x32_bf16 v[88:91], v[132:135], v[180:183], v[88:91]
	v_mfma_f32_16x16x32_bf16 v[76:79], v[124:127], v[208:211], v[76:79]
	v_mfma_f32_16x16x32_bf16 v[72:75], v[132:135], v[208:211], v[72:75]
	v_mfma_f32_16x16x32_bf16 v[116:119], v[136:139], v[152:155], v[116:119]
	v_mfma_f32_16x16x32_bf16 v[112:115], v[144:147], v[152:155], v[112:115]
	v_mfma_f32_16x16x32_bf16 v[100:103], v[136:139], v[160:163], v[100:103]
	v_mfma_f32_16x16x32_bf16 v[96:99], v[144:147], v[160:163], v[96:99]
	v_mfma_f32_16x16x32_bf16 v[84:87], v[136:139], v[176:179], v[84:87]
	v_mfma_f32_16x16x32_bf16 v[80:83], v[144:147], v[176:179], v[80:83]
	v_mfma_f32_16x16x32_bf16 v[68:71], v[136:139], v[184:187], v[68:71]
	v_mfma_f32_16x16x32_bf16 v[64:67], v[144:147], v[184:187], v[64:67]
	v_mfma_f32_16x16x32_bf16 v[116:119], v[140:143], v[156:159], v[116:119]
	v_mfma_f32_16x16x32_bf16 v[112:115], v[148:151], v[156:159], v[112:115]
	v_mfma_f32_16x16x32_bf16 v[100:103], v[140:143], v[172:175], v[100:103]
	v_mfma_f32_16x16x32_bf16 v[96:99], v[148:151], v[172:175], v[96:99]
	v_mfma_f32_16x16x32_bf16 v[84:87], v[140:143], v[180:183], v[84:87]
	v_mfma_f32_16x16x32_bf16 v[80:83], v[148:151], v[180:183], v[80:83]
	v_mfma_f32_16x16x32_bf16 v[68:71], v[140:143], v[208:211], v[68:71]
	v_mfma_f32_16x16x32_bf16 v[64:67], v[148:151], v[208:211], v[64:67]
	s_barrier
	s_add_i32 s3, s3, s89
	s_add_u32 s100, vcc_lo, 0x80
	s_addc_u32 s101, vcc_hi, 0
	s_mov_b32 m0, s3
	ds_read_b128 v[152:155], v248 offset:49152
	ds_read_b128 v[156:159], v248 offset:50176
	ds_read_b128 v[160:163], v248 offset:51200
	ds_read_b128 v[172:175], v248 offset:52224
	ds_read_b128 v[176:179], v248 offset:53248
	ds_read_b128 v[180:183], v248 offset:54272
	ds_read_b128 v[184:187], v248 offset:55296
	ds_read_b128 v[208:211], v248 offset:56320
	global_load_lds_dwordx4 v188, s[100:101]
	s_add_i32 m0, s3, 0x2000
	s_add_i32 s3, s33, s89
	global_load_lds_dwordx4 v206, s[100:101]
	s_add_u32 s36, s100, s92
	s_addc_u32 s37, s101, 0
	s_mov_b32 m0, s3
	s_nop 0
	global_load_lds_dwordx4 v188, s[36:37]
	s_add_i32 m0, s3, 0x2000
	s_nop 0
	global_load_lds_dwordx4 v206, s[36:37]
	s_add_u32 s100, s46, 0x80
	s_addc_u32 s101, s47, 0
	s_mov_b32 m0, s76
	s_nop 0
	global_load_lds_dwordx4 v202, s[100:101]
	s_mov_b32 m0, s77
	s_nop 0
	global_load_lds_dwordx4 v204, s[100:101]
	s_waitcnt vmcnt(8)
	s_waitcnt lgkmcnt(0)
	s_barrier
	v_mfma_f32_16x16x32_bf16 v[60:63], v[120:123], v[152:155], v[60:63]
	v_mfma_f32_16x16x32_bf16 v[56:59], v[128:131], v[152:155], v[56:59]
	v_mfma_f32_16x16x32_bf16 v[44:47], v[120:123], v[160:163], v[44:47]
	v_mfma_f32_16x16x32_bf16 v[40:43], v[128:131], v[160:163], v[40:43]
	v_mfma_f32_16x16x32_bf16 v[28:31], v[120:123], v[176:179], v[28:31]
	v_mfma_f32_16x16x32_bf16 v[24:27], v[128:131], v[176:179], v[24:27]
	v_mfma_f32_16x16x32_bf16 v[12:15], v[120:123], v[184:187], v[12:15]
	v_mfma_f32_16x16x32_bf16 v[8:11], v[128:131], v[184:187], v[8:11]
	v_mfma_f32_16x16x32_bf16 v[60:63], v[124:127], v[156:159], v[60:63]
	v_mfma_f32_16x16x32_bf16 v[56:59], v[132:135], v[156:159], v[56:59]
	v_mfma_f32_16x16x32_bf16 v[44:47], v[124:127], v[172:175], v[44:47]
	v_mfma_f32_16x16x32_bf16 v[40:43], v[132:135], v[172:175], v[40:43]
	v_mfma_f32_16x16x32_bf16 v[28:31], v[124:127], v[180:183], v[28:31]
	v_mfma_f32_16x16x32_bf16 v[24:27], v[132:135], v[180:183], v[24:27]
	v_mfma_f32_16x16x32_bf16 v[12:15], v[124:127], v[208:211], v[12:15]
	v_mfma_f32_16x16x32_bf16 v[8:11], v[132:135], v[208:211], v[8:11]
	v_mfma_f32_16x16x32_bf16 v[52:55], v[136:139], v[152:155], v[52:55]
	v_mfma_f32_16x16x32_bf16 v[48:51], v[144:147], v[152:155], v[48:51]
	v_mfma_f32_16x16x32_bf16 v[36:39], v[136:139], v[160:163], v[36:39]
	v_mfma_f32_16x16x32_bf16 v[32:35], v[144:147], v[160:163], v[32:35]
	v_mfma_f32_16x16x32_bf16 v[20:23], v[136:139], v[176:179], v[20:23]
	v_mfma_f32_16x16x32_bf16 v[16:19], v[144:147], v[176:179], v[16:19]
	v_mfma_f32_16x16x32_bf16 v[4:7], v[136:139], v[184:187], v[4:7]
	v_mfma_f32_16x16x32_bf16 v[0:3], v[144:147], v[184:187], v[0:3]
	v_mfma_f32_16x16x32_bf16 v[52:55], v[140:143], v[156:159], v[52:55]
	v_mfma_f32_16x16x32_bf16 v[48:51], v[148:151], v[156:159], v[48:51]
	v_mfma_f32_16x16x32_bf16 v[36:39], v[140:143], v[172:175], v[36:39]
	v_mfma_f32_16x16x32_bf16 v[32:35], v[148:151], v[172:175], v[32:35]
	v_mfma_f32_16x16x32_bf16 v[20:23], v[140:143], v[180:183], v[20:23]
	v_mfma_f32_16x16x32_bf16 v[16:19], v[148:151], v[180:183], v[16:19]
	v_mfma_f32_16x16x32_bf16 v[4:7], v[140:143], v[208:211], v[4:7]
	v_mfma_f32_16x16x32_bf16 v[0:3], v[148:151], v[208:211], v[0:3]
	s_barrier
	s_add_i32 s86, s86, 2
	s_cmp_ge_u32 s86, s98
	s_mov_b64 s[36:37], s[38:39]
	s_cbranch_scc1 .Lpeel_exit_resid
.LBB0_490:
	s_add_u32 s38, s36, 0x100
	s_addc_u32 s39, s37, 0
	s_cmp_ge_u32 s38, s24
	s_cselect_b32 s47, s24, 0
	s_cselect_b32 s46, 0, 0
	s_sub_u32 s38, s38, s47
	s_subb_u32 s39, s39, s46
	s_sub_u32 s47, s36, s47
	s_subb_u32 s46, s37, s46
	s_add_u32 vcc_lo, s34, s47
	s_addc_u32 vcc_hi, s35, s46
	s_add_u32 vcc_lo, vcc_lo, 0x100
	s_addc_u32 vcc_hi, vcc_hi, 0
	s_add_u32 s47, s30, s47
	s_addc_u32 s46, s31, s46
	s_add_u32 s69, s47, 0x100
	s_addc_u32 s3, s46, 0
	s_add_i32 s33, 0, 0x10000
	s_cmp_eq_u32 s99, s86
	s_cselect_b32 s47, s11, vcc_hi
	s_cselect_b32 s46, s10, vcc_lo
	s_cselect_b32 vcc_hi, s29, s3
	s_cselect_b32 vcc_lo, s28, s69
	s_add_i32 s3, 0, 0x14000
	ds_read_b128 v[120:123], v212
	ds_read_b128 v[124:127], v212 offset:1024
	ds_read_b128 v[128:131], v212 offset:2048
	ds_read_b128 v[132:135], v212 offset:3072
	ds_read_b128 v[136:139], v212 offset:16384
	ds_read_b128 v[140:143], v212 offset:17408
	ds_read_b128 v[144:147], v212 offset:18432
	ds_read_b128 v[148:151], v212 offset:19456
	s_add_u32 s36, s0, s36
	s_addc_u32 s37, s43, s37
	s_add_u32 s100, s36, 0x80
	s_addc_u32 s101, s37, 0
	s_add_i32 m0, s94, 0xc000
	ds_read_b128 v[152:155], v248
	ds_read_b128 v[156:159], v248 offset:1024
	ds_read_b128 v[160:163], v248 offset:2048
	ds_read_b128 v[172:175], v248 offset:3072
	ds_read_b128 v[176:179], v248 offset:4096
	ds_read_b128 v[180:183], v248 offset:5120
	ds_read_b128 v[184:187], v248 offset:6144
	ds_read_b128 v[208:211], v248 offset:7168
	global_load_lds_dwordx4 v202, s[100:101]
	s_add_i32 m0, s94, 0xe000
	s_nop 0
	global_load_lds_dwordx4 v204, s[100:101]
	s_waitcnt vmcnt(8)
	s_waitcnt lgkmcnt(0)
	s_barrier
	v_mfma_f32_16x16x32_bf16 v[168:171], v[120:123], v[152:155], v[168:171]
	v_mfma_f32_16x16x32_bf16 v[164:167], v[128:131], v[152:155], v[164:167]
	v_mfma_f32_16x16x32_bf16 v[108:111], v[120:123], v[160:163], v[108:111]
	v_mfma_f32_16x16x32_bf16 v[104:107], v[128:131], v[160:163], v[104:107]
	v_mfma_f32_16x16x32_bf16 v[92:95], v[120:123], v[176:179], v[92:95]
	v_mfma_f32_16x16x32_bf16 v[88:91], v[128:131], v[176:179], v[88:91]
	v_mfma_f32_16x16x32_bf16 v[76:79], v[120:123], v[184:187], v[76:79]
	v_mfma_f32_16x16x32_bf16 v[72:75], v[128:131], v[184:187], v[72:75]
	v_mfma_f32_16x16x32_bf16 v[168:171], v[124:127], v[156:159], v[168:171]
	v_mfma_f32_16x16x32_bf16 v[164:167], v[132:135], v[156:159], v[164:167]
	v_mfma_f32_16x16x32_bf16 v[108:111], v[124:127], v[172:175], v[108:111]
	v_mfma_f32_16x16x32_bf16 v[104:107], v[132:135], v[172:175], v[104:107]
	v_mfma_f32_16x16x32_bf16 v[92:95], v[124:127], v[180:183], v[92:95]
	v_mfma_f32_16x16x32_bf16 v[88:91], v[132:135], v[180:183], v[88:91]
	v_mfma_f32_16x16x32_bf16 v[76:79], v[124:127], v[208:211], v[76:79]
	v_mfma_f32_16x16x32_bf16 v[72:75], v[132:135], v[208:211], v[72:75]
	v_mfma_f32_16x16x32_bf16 v[116:119], v[136:139], v[152:155], v[116:119]
	v_mfma_f32_16x16x32_bf16 v[112:115], v[144:147], v[152:155], v[112:115]
	v_mfma_f32_16x16x32_bf16 v[100:103], v[136:139], v[160:163], v[100:103]
	v_mfma_f32_16x16x32_bf16 v[96:99], v[144:147], v[160:163], v[96:99]
	v_mfma_f32_16x16x32_bf16 v[84:87], v[136:139], v[176:179], v[84:87]
	v_mfma_f32_16x16x32_bf16 v[80:83], v[144:147], v[176:179], v[80:83]
	v_mfma_f32_16x16x32_bf16 v[68:71], v[136:139], v[184:187], v[68:71]
	v_mfma_f32_16x16x32_bf16 v[64:67], v[144:147], v[184:187], v[64:67]
	v_mfma_f32_16x16x32_bf16 v[116:119], v[140:143], v[156:159], v[116:119]
	v_mfma_f32_16x16x32_bf16 v[112:115], v[148:151], v[156:159], v[112:115]
	v_mfma_f32_16x16x32_bf16 v[100:103], v[140:143], v[172:175], v[100:103]
	v_mfma_f32_16x16x32_bf16 v[96:99], v[148:151], v[172:175], v[96:99]
	v_mfma_f32_16x16x32_bf16 v[84:87], v[140:143], v[180:183], v[84:87]
	v_mfma_f32_16x16x32_bf16 v[80:83], v[148:151], v[180:183], v[80:83]
	v_mfma_f32_16x16x32_bf16 v[68:71], v[140:143], v[208:211], v[68:71]
	v_mfma_f32_16x16x32_bf16 v[64:67], v[148:151], v[208:211], v[64:67]
	s_barrier
	s_add_i32 s33, s33, s89
	s_mov_b64 s[100:101], vcc
	s_mov_b32 m0, s33
	ds_read_b128 v[152:155], v248 offset:16384
	ds_read_b128 v[156:159], v248 offset:17408
	ds_read_b128 v[160:163], v248 offset:18432
	ds_read_b128 v[172:175], v248 offset:19456
	ds_read_b128 v[176:179], v248 offset:20480
	ds_read_b128 v[180:183], v248 offset:21504
	ds_read_b128 v[184:187], v248 offset:22528
	ds_read_b128 v[208:211], v248 offset:23552
	global_load_lds_dwordx4 v188, s[100:101]
	s_add_i32 m0, s33, 0x2000
	s_add_u32 s36, vcc_lo, s92
	s_addc_u32 s37, vcc_hi, 0
	s_add_i32 s3, s3, s89
	global_load_lds_dwordx4 v206, s[100:101]
	s_mov_b32 m0, s3
	s_nop 0
	global_load_lds_dwordx4 v188, s[36:37]
	s_add_i32 m0, s3, 0x2000
	s_nop 0
	global_load_lds_dwordx4 v206, s[36:37]
	s_mov_b32 m0, s94
	s_nop 0
	global_load_lds_dwordx4 v202, s[46:47]
	s_mov_b32 m0, s95
	s_nop 0
	global_load_lds_dwordx4 v204, s[46:47]
	s_waitcnt vmcnt(8)
	s_waitcnt lgkmcnt(0)
	s_barrier
	v_mfma_f32_16x16x32_bf16 v[60:63], v[120:123], v[152:155], v[60:63]
	v_mfma_f32_16x16x32_bf16 v[56:59], v[128:131], v[152:155], v[56:59]
	v_mfma_f32_16x16x32_bf16 v[44:47], v[120:123], v[160:163], v[44:47]
	v_mfma_f32_16x16x32_bf16 v[40:43], v[128:131], v[160:163], v[40:43]
	v_mfma_f32_16x16x32_bf16 v[28:31], v[120:123], v[176:179], v[28:31]
	v_mfma_f32_16x16x32_bf16 v[24:27], v[128:131], v[176:179], v[24:27]
	v_mfma_f32_16x16x32_bf16 v[12:15], v[120:123], v[184:187], v[12:15]
	v_mfma_f32_16x16x32_bf16 v[8:11], v[128:131], v[184:187], v[8:11]
	v_mfma_f32_16x16x32_bf16 v[60:63], v[124:127], v[156:159], v[60:63]
	v_mfma_f32_16x16x32_bf16 v[56:59], v[132:135], v[156:159], v[56:59]
	v_mfma_f32_16x16x32_bf16 v[44:47], v[124:127], v[172:175], v[44:47]
	v_mfma_f32_16x16x32_bf16 v[40:43], v[132:135], v[172:175], v[40:43]
	v_mfma_f32_16x16x32_bf16 v[28:31], v[124:127], v[180:183], v[28:31]
	v_mfma_f32_16x16x32_bf16 v[24:27], v[132:135], v[180:183], v[24:27]
	v_mfma_f32_16x16x32_bf16 v[12:15], v[124:127], v[208:211], v[12:15]
	v_mfma_f32_16x16x32_bf16 v[8:11], v[132:135], v[208:211], v[8:11]
	v_mfma_f32_16x16x32_bf16 v[52:55], v[136:139], v[152:155], v[52:55]
	v_mfma_f32_16x16x32_bf16 v[48:51], v[144:147], v[152:155], v[48:51]
	v_mfma_f32_16x16x32_bf16 v[36:39], v[136:139], v[160:163], v[36:39]
	v_mfma_f32_16x16x32_bf16 v[32:35], v[144:147], v[160:163], v[32:35]
	v_mfma_f32_16x16x32_bf16 v[20:23], v[136:139], v[176:179], v[20:23]
	v_mfma_f32_16x16x32_bf16 v[16:19], v[144:147], v[176:179], v[16:19]
	v_mfma_f32_16x16x32_bf16 v[4:7], v[136:139], v[184:187], v[4:7]
	v_mfma_f32_16x16x32_bf16 v[0:3], v[144:147], v[184:187], v[0:3]
	v_mfma_f32_16x16x32_bf16 v[52:55], v[140:143], v[156:159], v[52:55]
	v_mfma_f32_16x16x32_bf16 v[48:51], v[148:151], v[156:159], v[48:51]
	v_mfma_f32_16x16x32_bf16 v[36:39], v[140:143], v[172:175], v[36:39]
	v_mfma_f32_16x16x32_bf16 v[32:35], v[148:151], v[172:175], v[32:35]
	v_mfma_f32_16x16x32_bf16 v[20:23], v[140:143], v[180:183], v[20:23]
	v_mfma_f32_16x16x32_bf16 v[16:19], v[148:151], v[180:183], v[16:19]
	v_mfma_f32_16x16x32_bf16 v[4:7], v[140:143], v[208:211], v[4:7]
	v_mfma_f32_16x16x32_bf16 v[0:3], v[148:151], v[208:211], v[0:3]
	s_barrier
	s_add_i32 s3, 0, 0x18000
	s_add_i32 s33, 0, 0x1c000
	ds_read_b128 v[120:123], v212 offset:32768
	ds_read_b128 v[124:127], v212 offset:33792
	ds_read_b128 v[128:131], v212 offset:34816
	ds_read_b128 v[132:135], v212 offset:35840
	ds_read_b128 v[136:139], v212 offset:49152
	ds_read_b128 v[140:143], v212 offset:50176
	ds_read_b128 v[144:147], v212 offset:51200
	ds_read_b128 v[148:151], v212 offset:52224
	s_add_u32 s36, s46, s92
	s_addc_u32 s37, s47, 0
	s_mov_b32 m0, s96
	ds_read_b128 v[152:155], v248 offset:32768
	ds_read_b128 v[156:159], v248 offset:33792
	ds_read_b128 v[160:163], v248 offset:34816
	ds_read_b128 v[172:175], v248 offset:35840
	ds_read_b128 v[176:179], v248 offset:36864
	ds_read_b128 v[180:183], v248 offset:37888
	ds_read_b128 v[184:187], v248 offset:38912
	ds_read_b128 v[208:211], v248 offset:39936
	global_load_lds_dwordx4 v202, s[36:37]
	s_mov_b32 m0, s97
	s_nop 0
	global_load_lds_dwordx4 v204, s[36:37]
	s_waitcnt vmcnt(8)
	s_waitcnt lgkmcnt(0)
	s_barrier
	v_mfma_f32_16x16x32_bf16 v[168:171], v[120:123], v[152:155], v[168:171]
	v_mfma_f32_16x16x32_bf16 v[164:167], v[128:131], v[152:155], v[164:167]
	v_mfma_f32_16x16x32_bf16 v[108:111], v[120:123], v[160:163], v[108:111]
	v_mfma_f32_16x16x32_bf16 v[104:107], v[128:131], v[160:163], v[104:107]
	v_mfma_f32_16x16x32_bf16 v[92:95], v[120:123], v[176:179], v[92:95]
	v_mfma_f32_16x16x32_bf16 v[88:91], v[128:131], v[176:179], v[88:91]
	v_mfma_f32_16x16x32_bf16 v[76:79], v[120:123], v[184:187], v[76:79]
	v_mfma_f32_16x16x32_bf16 v[72:75], v[128:131], v[184:187], v[72:75]
	v_mfma_f32_16x16x32_bf16 v[168:171], v[124:127], v[156:159], v[168:171]
	v_mfma_f32_16x16x32_bf16 v[164:167], v[132:135], v[156:159], v[164:167]
	v_mfma_f32_16x16x32_bf16 v[108:111], v[124:127], v[172:175], v[108:111]
	v_mfma_f32_16x16x32_bf16 v[104:107], v[132:135], v[172:175], v[104:107]
	v_mfma_f32_16x16x32_bf16 v[92:95], v[124:127], v[180:183], v[92:95]
	v_mfma_f32_16x16x32_bf16 v[88:91], v[132:135], v[180:183], v[88:91]
	v_mfma_f32_16x16x32_bf16 v[76:79], v[124:127], v[208:211], v[76:79]
	v_mfma_f32_16x16x32_bf16 v[72:75], v[132:135], v[208:211], v[72:75]
	v_mfma_f32_16x16x32_bf16 v[116:119], v[136:139], v[152:155], v[116:119]
	v_mfma_f32_16x16x32_bf16 v[112:115], v[144:147], v[152:155], v[112:115]
	v_mfma_f32_16x16x32_bf16 v[100:103], v[136:139], v[160:163], v[100:103]
	v_mfma_f32_16x16x32_bf16 v[96:99], v[144:147], v[160:163], v[96:99]
	v_mfma_f32_16x16x32_bf16 v[84:87], v[136:139], v[176:179], v[84:87]
	v_mfma_f32_16x16x32_bf16 v[80:83], v[144:147], v[176:179], v[80:83]
	v_mfma_f32_16x16x32_bf16 v[68:71], v[136:139], v[184:187], v[68:71]
	v_mfma_f32_16x16x32_bf16 v[64:67], v[144:147], v[184:187], v[64:67]
	v_mfma_f32_16x16x32_bf16 v[116:119], v[140:143], v[156:159], v[116:119]
	v_mfma_f32_16x16x32_bf16 v[112:115], v[148:151], v[156:159], v[112:115]
	v_mfma_f32_16x16x32_bf16 v[100:103], v[140:143], v[172:175], v[100:103]
	v_mfma_f32_16x16x32_bf16 v[96:99], v[148:151], v[172:175], v[96:99]
	v_mfma_f32_16x16x32_bf16 v[84:87], v[140:143], v[180:183], v[84:87]
	v_mfma_f32_16x16x32_bf16 v[80:83], v[148:151], v[180:183], v[80:83]
	v_mfma_f32_16x16x32_bf16 v[68:71], v[140:143], v[208:211], v[68:71]
	v_mfma_f32_16x16x32_bf16 v[64:67], v[148:151], v[208:211], v[64:67]
	s_barrier
	s_add_i32 s3, s3, s89
	s_add_u32 s100, vcc_lo, 0x80
	s_addc_u32 s101, vcc_hi, 0
	s_mov_b32 m0, s3
	ds_read_b128 v[152:155], v248 offset:49152
	ds_read_b128 v[156:159], v248 offset:50176
	ds_read_b128 v[160:163], v248 offset:51200
	ds_read_b128 v[172:175], v248 offset:52224
	ds_read_b128 v[176:179], v248 offset:53248
	ds_read_b128 v[180:183], v248 offset:54272
	ds_read_b128 v[184:187], v248 offset:55296
	ds_read_b128 v[208:211], v248 offset:56320
	global_load_lds_dwordx4 v188, s[100:101]
	s_add_i32 m0, s3, 0x2000
	s_add_i32 s3, s33, s89
	global_load_lds_dwordx4 v206, s[100:101]
	s_add_u32 s36, s100, s92
	s_addc_u32 s37, s101, 0
	s_mov_b32 m0, s3
	s_nop 0
	global_load_lds_dwordx4 v188, s[36:37]
	s_add_i32 m0, s3, 0x2000
	s_nop 0
	global_load_lds_dwordx4 v206, s[36:37]
	s_add_u32 s100, s46, 0x80
	s_addc_u32 s101, s47, 0
	s_mov_b32 m0, s76
	s_nop 0
	global_load_lds_dwordx4 v202, s[100:101]
	s_mov_b32 m0, s77
	s_nop 0
	global_load_lds_dwordx4 v204, s[100:101]
	s_waitcnt vmcnt(8)
	s_waitcnt lgkmcnt(0)
	s_barrier
	v_mfma_f32_16x16x32_bf16 v[60:63], v[120:123], v[152:155], v[60:63]
	v_mfma_f32_16x16x32_bf16 v[56:59], v[128:131], v[152:155], v[56:59]
	v_mfma_f32_16x16x32_bf16 v[44:47], v[120:123], v[160:163], v[44:47]
	v_mfma_f32_16x16x32_bf16 v[40:43], v[128:131], v[160:163], v[40:43]
	v_mfma_f32_16x16x32_bf16 v[28:31], v[120:123], v[176:179], v[28:31]
	v_mfma_f32_16x16x32_bf16 v[24:27], v[128:131], v[176:179], v[24:27]
	v_mfma_f32_16x16x32_bf16 v[12:15], v[120:123], v[184:187], v[12:15]
	v_mfma_f32_16x16x32_bf16 v[8:11], v[128:131], v[184:187], v[8:11]
	v_mfma_f32_16x16x32_bf16 v[60:63], v[124:127], v[156:159], v[60:63]
	v_mfma_f32_16x16x32_bf16 v[56:59], v[132:135], v[156:159], v[56:59]
	v_mfma_f32_16x16x32_bf16 v[44:47], v[124:127], v[172:175], v[44:47]
	v_mfma_f32_16x16x32_bf16 v[40:43], v[132:135], v[172:175], v[40:43]
	v_mfma_f32_16x16x32_bf16 v[28:31], v[124:127], v[180:183], v[28:31]
	v_mfma_f32_16x16x32_bf16 v[24:27], v[132:135], v[180:183], v[24:27]
	v_mfma_f32_16x16x32_bf16 v[12:15], v[124:127], v[208:211], v[12:15]
	v_mfma_f32_16x16x32_bf16 v[8:11], v[132:135], v[208:211], v[8:11]
	v_mfma_f32_16x16x32_bf16 v[52:55], v[136:139], v[152:155], v[52:55]
	v_mfma_f32_16x16x32_bf16 v[48:51], v[144:147], v[152:155], v[48:51]
	v_mfma_f32_16x16x32_bf16 v[36:39], v[136:139], v[160:163], v[36:39]
	v_mfma_f32_16x16x32_bf16 v[32:35], v[144:147], v[160:163], v[32:35]
	v_mfma_f32_16x16x32_bf16 v[20:23], v[136:139], v[176:179], v[20:23]
	v_mfma_f32_16x16x32_bf16 v[16:19], v[144:147], v[176:179], v[16:19]
	v_mfma_f32_16x16x32_bf16 v[4:7], v[136:139], v[184:187], v[4:7]
	v_mfma_f32_16x16x32_bf16 v[0:3], v[144:147], v[184:187], v[0:3]
	v_mfma_f32_16x16x32_bf16 v[52:55], v[140:143], v[156:159], v[52:55]
	v_mfma_f32_16x16x32_bf16 v[48:51], v[148:151], v[156:159], v[48:51]
	v_mfma_f32_16x16x32_bf16 v[36:39], v[140:143], v[172:175], v[36:39]
	v_mfma_f32_16x16x32_bf16 v[32:35], v[148:151], v[172:175], v[32:35]
	v_mfma_f32_16x16x32_bf16 v[20:23], v[140:143], v[180:183], v[20:23]
	v_mfma_f32_16x16x32_bf16 v[16:19], v[148:151], v[180:183], v[16:19]
	v_mfma_f32_16x16x32_bf16 v[4:7], v[140:143], v[208:211], v[4:7]
	v_mfma_f32_16x16x32_bf16 v[0:3], v[148:151], v[208:211], v[0:3]
	s_barrier
	s_add_i32 s86, s86, 2
	s_cmp_ge_u32 s86, s98
	s_mov_b64 s[36:37], s[38:39]
	s_cbranch_scc0 .LBB0_490

.Lprio_sw:
	s_add_u32 s34, s30, 0x100
	s_addc_u32 s35, s31, 0
	s_add_u32 s38, s30, 0xfffff900
	s_addc_u32 s39, s31, -1
	s_cmp_gt_u32 s34, 0x7ff
	s_cselect_b32 s34, s38, s34
	s_cselect_b32 s35, s39, s35
	s_add_u32 s36, s28, s34
	s_addc_u32 s37, s29, s35
	s_add_u32 s76, s26, s34
	s_addc_u32 s77, s27, s35
	s_add_i32 s86, 0, 0x10000
	s_cmp_eq_u32 s43, 12
	s_cselect_b32 s39, s19, s37
	s_cselect_b32 s38, s25, s36
	s_cselect_b32 s37, s0, s77
	s_cselect_b32 s36, s17, s76
	s_add_i32 s76, 0, 0x14000
	ds_read_b128 v[96:99], v186
	ds_read_b128 v[150:153], v186 offset:1024
	ds_read_b128 v[154:157], v186 offset:2048
	ds_read_b128 v[158:161], v186 offset:3072
	ds_read_b128 v[162:165], v186 offset:16384
	ds_read_b128 v[166:169], v186 offset:17408
	ds_read_b128 v[170:173], v186 offset:18432
	ds_read_b128 v[174:177], v186 offset:19456
	s_add_u32 s30, s28, s30
	s_addc_u32 s31, s29, s31
	s_add_u32 s30, s30, 0x40080
	s_addc_u32 s31, s31, 0
	s_add_i32 m0, s60, 0xc000
	ds_read_b128 v[178:181], v149
	ds_read_b128 v[182:185], v149 offset:1024
	ds_read_b128 v[202:205], v149 offset:2048
	ds_read_b128 v[206:209], v149 offset:3072
	ds_read_b128 v[210:213], v149 offset:4096
	ds_read_b128 v[214:217], v149 offset:5120
	ds_read_b128 v[218:221], v149 offset:6144
	ds_read_b128 v[222:225], v149 offset:7168
	global_load_lds_dwordx4 v136, s[30:31]
	s_add_i32 m0, s60, 0xe000
	s_nop 0
	global_load_lds_dwordx4 v134, s[30:31]
	s_waitcnt vmcnt(8)
	s_waitcnt lgkmcnt(0)
	s_barrier
	v_mfma_f32_16x16x32_bf16 v[128:131], v[96:99], v[178:181], 0
	v_mfma_f32_16x16x32_bf16 v[120:123], v[154:157], v[178:181], 0
	v_mfma_f32_16x16x32_bf16 v[112:115], v[96:99], v[202:205], 0
	v_mfma_f32_16x16x32_bf16 v[104:107], v[154:157], v[202:205], 0
	v_mfma_f32_16x16x32_bf16 v[92:95], v[96:99], v[210:213], 0
	v_mfma_f32_16x16x32_bf16 v[84:87], v[154:157], v[210:213], 0
	v_mfma_f32_16x16x32_bf16 v[76:79], v[96:99], v[218:221], 0
	v_mfma_f32_16x16x32_bf16 v[68:71], v[154:157], v[218:221], 0
	v_mfma_f32_16x16x32_bf16 v[128:131], v[150:153], v[182:185], v[128:131]
	v_mfma_f32_16x16x32_bf16 v[120:123], v[158:161], v[182:185], v[120:123]
	v_mfma_f32_16x16x32_bf16 v[112:115], v[150:153], v[206:209], v[112:115]
	v_mfma_f32_16x16x32_bf16 v[104:107], v[158:161], v[206:209], v[104:107]
	v_mfma_f32_16x16x32_bf16 v[92:95], v[150:153], v[214:217], v[92:95]
	v_mfma_f32_16x16x32_bf16 v[84:87], v[158:161], v[214:217], v[84:87]
	v_mfma_f32_16x16x32_bf16 v[76:79], v[150:153], v[222:225], v[76:79]
	v_mfma_f32_16x16x32_bf16 v[68:71], v[158:161], v[222:225], v[68:71]
	v_mfma_f32_16x16x32_bf16 v[124:127], v[162:165], v[178:181], 0
	v_mfma_f32_16x16x32_bf16 v[116:119], v[170:173], v[178:181], 0
	v_mfma_f32_16x16x32_bf16 v[108:111], v[162:165], v[202:205], 0
	v_mfma_f32_16x16x32_bf16 v[100:103], v[170:173], v[202:205], 0
	v_mfma_f32_16x16x32_bf16 v[88:91], v[162:165], v[210:213], 0
	v_mfma_f32_16x16x32_bf16 v[80:83], v[170:173], v[210:213], 0
	v_mfma_f32_16x16x32_bf16 v[72:75], v[162:165], v[218:221], 0
	v_mfma_f32_16x16x32_bf16 v[64:67], v[170:173], v[218:221], 0
	v_mfma_f32_16x16x32_bf16 v[124:127], v[166:169], v[182:185], v[124:127]
	v_mfma_f32_16x16x32_bf16 v[116:119], v[174:177], v[182:185], v[116:119]
	v_mfma_f32_16x16x32_bf16 v[108:111], v[166:169], v[206:209], v[108:111]
	v_mfma_f32_16x16x32_bf16 v[100:103], v[174:177], v[206:209], v[100:103]
	v_mfma_f32_16x16x32_bf16 v[88:91], v[166:169], v[214:217], v[88:91]
	v_mfma_f32_16x16x32_bf16 v[80:83], v[174:177], v[214:217], v[80:83]
	v_mfma_f32_16x16x32_bf16 v[72:75], v[166:169], v[222:225], v[72:75]
	v_mfma_f32_16x16x32_bf16 v[64:67], v[174:177], v[222:225], v[64:67]
	s_barrier
	s_add_i32 s30, s86, s56
	s_mov_b32 m0, s30
	ds_read_b128 v[178:181], v149 offset:16384
	ds_read_b128 v[182:185], v149 offset:17408
	ds_read_b128 v[202:205], v149 offset:18432
	ds_read_b128 v[206:209], v149 offset:19456
	ds_read_b128 v[210:213], v149 offset:20480
	ds_read_b128 v[214:217], v149 offset:21504
	ds_read_b128 v[218:221], v149 offset:22528
	ds_read_b128 v[222:225], v149 offset:23552
	global_load_lds_dwordx4 v188, s[36:37]
	s_add_i32 m0, s30, 0x2000
	s_add_u32 s30, s36, 0x40000
	s_addc_u32 s31, s37, 0
	s_add_i32 s76, s76, s56
	global_load_lds_dwordx4 v132, s[36:37]
	s_mov_b32 m0, s76
	s_nop 0
	global_load_lds_dwordx4 v188, s[30:31]
	s_add_i32 m0, s76, 0x2000
	s_nop 0
	global_load_lds_dwordx4 v132, s[30:31]
	s_mov_b32 m0, s60
	s_nop 0
	global_load_lds_dwordx4 v136, s[38:39]
	s_mov_b32 m0, s71
	s_nop 0
	global_load_lds_dwordx4 v134, s[38:39]
	s_waitcnt vmcnt(8)
	s_waitcnt lgkmcnt(0)
	s_barrier
	v_mfma_f32_16x16x32_bf16 v[60:63], v[96:99], v[178:181], 0
	v_mfma_f32_16x16x32_bf16 v[52:55], v[154:157], v[178:181], 0
	v_mfma_f32_16x16x32_bf16 v[44:47], v[96:99], v[202:205], 0
	v_mfma_f32_16x16x32_bf16 v[36:39], v[154:157], v[202:205], 0
	v_mfma_f32_16x16x32_bf16 v[28:31], v[96:99], v[210:213], 0
	v_mfma_f32_16x16x32_bf16 v[20:23], v[154:157], v[210:213], 0
	v_mfma_f32_16x16x32_bf16 v[12:15], v[96:99], v[218:221], 0
	v_mfma_f32_16x16x32_bf16 v[4:7], v[154:157], v[218:221], 0
	v_mfma_f32_16x16x32_bf16 v[60:63], v[150:153], v[182:185], v[60:63]
	v_mfma_f32_16x16x32_bf16 v[52:55], v[158:161], v[182:185], v[52:55]
	v_mfma_f32_16x16x32_bf16 v[44:47], v[150:153], v[206:209], v[44:47]
	v_mfma_f32_16x16x32_bf16 v[36:39], v[158:161], v[206:209], v[36:39]
	v_mfma_f32_16x16x32_bf16 v[28:31], v[150:153], v[214:217], v[28:31]
	v_mfma_f32_16x16x32_bf16 v[20:23], v[158:161], v[214:217], v[20:23]
	v_mfma_f32_16x16x32_bf16 v[12:15], v[150:153], v[222:225], v[12:15]
	v_mfma_f32_16x16x32_bf16 v[4:7], v[158:161], v[222:225], v[4:7]
	v_mfma_f32_16x16x32_bf16 v[56:59], v[162:165], v[178:181], 0
	v_mfma_f32_16x16x32_bf16 v[48:51], v[170:173], v[178:181], 0
	v_mfma_f32_16x16x32_bf16 v[40:43], v[162:165], v[202:205], 0
	v_mfma_f32_16x16x32_bf16 v[32:35], v[170:173], v[202:205], 0
	v_mfma_f32_16x16x32_bf16 v[24:27], v[162:165], v[210:213], 0
	v_mfma_f32_16x16x32_bf16 v[16:19], v[170:173], v[210:213], 0
	v_mfma_f32_16x16x32_bf16 v[8:11], v[162:165], v[218:221], 0
	v_mfma_f32_16x16x32_bf16 v[0:3], v[170:173], v[218:221], 0
	v_mfma_f32_16x16x32_bf16 v[56:59], v[166:169], v[182:185], v[56:59]
	v_mfma_f32_16x16x32_bf16 v[48:51], v[174:177], v[182:185], v[48:51]
	v_mfma_f32_16x16x32_bf16 v[40:43], v[166:169], v[206:209], v[40:43]
	v_mfma_f32_16x16x32_bf16 v[32:35], v[174:177], v[206:209], v[32:35]
	v_mfma_f32_16x16x32_bf16 v[24:27], v[166:169], v[214:217], v[24:27]
	v_mfma_f32_16x16x32_bf16 v[16:19], v[174:177], v[214:217], v[16:19]
	v_mfma_f32_16x16x32_bf16 v[8:11], v[166:169], v[222:225], v[8:11]
	v_mfma_f32_16x16x32_bf16 v[0:3], v[174:177], v[222:225], v[0:3]
	s_barrier
	s_add_i32 s76, 0, 0x18000
	s_add_i32 s77, 0, 0x1c000
	ds_read_b128 v[96:99], v186 offset:32768
	ds_read_b128 v[150:153], v186 offset:33792
	ds_read_b128 v[154:157], v186 offset:34816
	ds_read_b128 v[158:161], v186 offset:35840
	ds_read_b128 v[162:165], v186 offset:49152
	ds_read_b128 v[166:169], v186 offset:50176
	ds_read_b128 v[170:173], v186 offset:51200
	ds_read_b128 v[174:177], v186 offset:52224
	s_add_u32 s30, s38, 0x40000
	s_addc_u32 s31, s39, 0
	s_mov_b32 m0, s87
	ds_read_b128 v[178:181], v149 offset:32768
	ds_read_b128 v[182:185], v149 offset:33792
	ds_read_b128 v[202:205], v149 offset:34816
	ds_read_b128 v[206:209], v149 offset:35840
	ds_read_b128 v[210:213], v149 offset:36864
	ds_read_b128 v[214:217], v149 offset:37888
	ds_read_b128 v[218:221], v149 offset:38912
	ds_read_b128 v[222:225], v149 offset:39936
	global_load_lds_dwordx4 v136, s[30:31]
	s_mov_b32 m0, s89
	s_nop 0
	global_load_lds_dwordx4 v134, s[30:31]
	s_waitcnt vmcnt(8)
	s_waitcnt lgkmcnt(0)
	s_barrier
	v_mfma_f32_16x16x32_bf16 v[128:131], v[96:99], v[178:181], v[128:131]
	v_mfma_f32_16x16x32_bf16 v[120:123], v[154:157], v[178:181], v[120:123]
	v_mfma_f32_16x16x32_bf16 v[112:115], v[96:99], v[202:205], v[112:115]
	v_mfma_f32_16x16x32_bf16 v[104:107], v[154:157], v[202:205], v[104:107]
	v_mfma_f32_16x16x32_bf16 v[92:95], v[96:99], v[210:213], v[92:95]
	v_mfma_f32_16x16x32_bf16 v[84:87], v[154:157], v[210:213], v[84:87]
	v_mfma_f32_16x16x32_bf16 v[76:79], v[96:99], v[218:221], v[76:79]
	v_mfma_f32_16x16x32_bf16 v[68:71], v[154:157], v[218:221], v[68:71]
	v_mfma_f32_16x16x32_bf16 v[128:131], v[150:153], v[182:185], v[128:131]
	v_mfma_f32_16x16x32_bf16 v[120:123], v[158:161], v[182:185], v[120:123]
	v_mfma_f32_16x16x32_bf16 v[112:115], v[150:153], v[206:209], v[112:115]
	v_mfma_f32_16x16x32_bf16 v[104:107], v[158:161], v[206:209], v[104:107]
	v_mfma_f32_16x16x32_bf16 v[92:95], v[150:153], v[214:217], v[92:95]
	v_mfma_f32_16x16x32_bf16 v[84:87], v[158:161], v[214:217], v[84:87]
	v_mfma_f32_16x16x32_bf16 v[76:79], v[150:153], v[222:225], v[76:79]
	v_mfma_f32_16x16x32_bf16 v[68:71], v[158:161], v[222:225], v[68:71]
	v_mfma_f32_16x16x32_bf16 v[124:127], v[162:165], v[178:181], v[124:127]
	v_mfma_f32_16x16x32_bf16 v[116:119], v[170:173], v[178:181], v[116:119]
	v_mfma_f32_16x16x32_bf16 v[108:111], v[162:165], v[202:205], v[108:111]
	v_mfma_f32_16x16x32_bf16 v[100:103], v[170:173], v[202:205], v[100:103]
	v_mfma_f32_16x16x32_bf16 v[88:91], v[162:165], v[210:213], v[88:91]
	v_mfma_f32_16x16x32_bf16 v[80:83], v[170:173], v[210:213], v[80:83]
	v_mfma_f32_16x16x32_bf16 v[72:75], v[162:165], v[218:221], v[72:75]
	v_mfma_f32_16x16x32_bf16 v[64:67], v[170:173], v[218:221], v[64:67]
	v_mfma_f32_16x16x32_bf16 v[124:127], v[166:169], v[182:185], v[124:127]
	v_mfma_f32_16x16x32_bf16 v[116:119], v[174:177], v[182:185], v[116:119]
	v_mfma_f32_16x16x32_bf16 v[108:111], v[166:169], v[206:209], v[108:111]
	v_mfma_f32_16x16x32_bf16 v[100:103], v[174:177], v[206:209], v[100:103]
	v_mfma_f32_16x16x32_bf16 v[88:91], v[166:169], v[214:217], v[88:91]
	v_mfma_f32_16x16x32_bf16 v[80:83], v[174:177], v[214:217], v[80:83]
	v_mfma_f32_16x16x32_bf16 v[72:75], v[166:169], v[222:225], v[72:75]
	v_mfma_f32_16x16x32_bf16 v[64:67], v[174:177], v[222:225], v[64:67]
	s_barrier
	s_add_i32 s30, s76, s56
	s_add_u32 s100, s36, 0x80
	s_addc_u32 s101, s37, 0
	s_mov_b32 m0, s30
	ds_read_b128 v[178:181], v149 offset:49152
	ds_read_b128 v[182:185], v149 offset:50176
	ds_read_b128 v[202:205], v149 offset:51200
	ds_read_b128 v[206:209], v149 offset:52224
	ds_read_b128 v[210:213], v149 offset:53248
	ds_read_b128 v[214:217], v149 offset:54272
	ds_read_b128 v[218:221], v149 offset:55296
	ds_read_b128 v[222:225], v149 offset:56320
	global_load_lds_dwordx4 v188, s[100:101]
	s_add_i32 m0, s30, 0x2000
	s_add_u32 s30, s36, 0x40080
	s_addc_u32 s31, s37, 0
	s_add_i32 s36, s77, s56
	global_load_lds_dwordx4 v132, s[100:101]
	s_mov_b32 m0, s36
	s_nop 0
	global_load_lds_dwordx4 v188, s[30:31]
	s_add_i32 m0, s36, 0x2000
	s_nop 0
	global_load_lds_dwordx4 v132, s[30:31]
	s_add_u32 s100, s38, 0x80
	s_addc_u32 s101, s39, 0
	s_mov_b32 m0, s90
	s_nop 0
	global_load_lds_dwordx4 v136, s[100:101]
	s_mov_b32 m0, s91
	s_nop 0
	global_load_lds_dwordx4 v134, s[100:101]
	s_waitcnt vmcnt(8)
	s_waitcnt lgkmcnt(0)
	s_barrier
	v_mfma_f32_16x16x32_bf16 v[60:63], v[96:99], v[178:181], v[60:63]
	v_mfma_f32_16x16x32_bf16 v[52:55], v[154:157], v[178:181], v[52:55]
	v_mfma_f32_16x16x32_bf16 v[44:47], v[96:99], v[202:205], v[44:47]
	v_mfma_f32_16x16x32_bf16 v[36:39], v[154:157], v[202:205], v[36:39]
	v_mfma_f32_16x16x32_bf16 v[28:31], v[96:99], v[210:213], v[28:31]
	v_mfma_f32_16x16x32_bf16 v[20:23], v[154:157], v[210:213], v[20:23]
	v_mfma_f32_16x16x32_bf16 v[12:15], v[96:99], v[218:221], v[12:15]
	v_mfma_f32_16x16x32_bf16 v[4:7], v[154:157], v[218:221], v[4:7]
	v_mfma_f32_16x16x32_bf16 v[60:63], v[150:153], v[182:185], v[60:63]
	v_mfma_f32_16x16x32_bf16 v[52:55], v[158:161], v[182:185], v[52:55]
	v_mfma_f32_16x16x32_bf16 v[44:47], v[150:153], v[206:209], v[44:47]
	v_mfma_f32_16x16x32_bf16 v[36:39], v[158:161], v[206:209], v[36:39]
	v_mfma_f32_16x16x32_bf16 v[28:31], v[150:153], v[214:217], v[28:31]
	v_mfma_f32_16x16x32_bf16 v[20:23], v[158:161], v[214:217], v[20:23]
	v_mfma_f32_16x16x32_bf16 v[12:15], v[150:153], v[222:225], v[12:15]
	v_mfma_f32_16x16x32_bf16 v[4:7], v[158:161], v[222:225], v[4:7]
	v_mfma_f32_16x16x32_bf16 v[56:59], v[162:165], v[178:181], v[56:59]
	v_mfma_f32_16x16x32_bf16 v[48:51], v[170:173], v[178:181], v[48:51]
	v_mfma_f32_16x16x32_bf16 v[40:43], v[162:165], v[202:205], v[40:43]
	v_mfma_f32_16x16x32_bf16 v[32:35], v[170:173], v[202:205], v[32:35]
	v_mfma_f32_16x16x32_bf16 v[24:27], v[162:165], v[210:213], v[24:27]
	v_mfma_f32_16x16x32_bf16 v[16:19], v[170:173], v[210:213], v[16:19]
	v_mfma_f32_16x16x32_bf16 v[8:11], v[162:165], v[218:221], v[8:11]
	v_mfma_f32_16x16x32_bf16 v[0:3], v[170:173], v[218:221], v[0:3]
	v_mfma_f32_16x16x32_bf16 v[56:59], v[166:169], v[182:185], v[56:59]
	v_mfma_f32_16x16x32_bf16 v[48:51], v[174:177], v[182:185], v[48:51]
	v_mfma_f32_16x16x32_bf16 v[40:43], v[166:169], v[206:209], v[40:43]
	v_mfma_f32_16x16x32_bf16 v[32:35], v[174:177], v[206:209], v[32:35]
	v_mfma_f32_16x16x32_bf16 v[24:27], v[166:169], v[214:217], v[24:27]
	v_mfma_f32_16x16x32_bf16 v[16:19], v[174:177], v[214:217], v[16:19]
	v_mfma_f32_16x16x32_bf16 v[8:11], v[166:169], v[222:225], v[8:11]
	v_mfma_f32_16x16x32_bf16 v[0:3], v[174:177], v[222:225], v[0:3]
	s_barrier
	s_add_i32 s43, s43, 2
	s_cmp_gt_u32 s43, 13
	s_mov_b64 s[30:31], s[34:35]
	s_cbranch_scc1 .Lpeel_exit_swiglu
.LBB0_528:
	s_add_u32 s34, s30, 0x100
	s_addc_u32 s35, s31, 0
	s_add_u32 s38, s30, 0xfffff900
	s_addc_u32 s39, s31, -1
	s_cmp_gt_u32 s34, 0x7ff
	s_cselect_b32 s34, s38, s34
	s_cselect_b32 s35, s39, s35
	s_add_u32 s36, s28, s34
	s_addc_u32 s37, s29, s35
	s_add_u32 s76, s26, s34
	s_addc_u32 s77, s27, s35
	s_add_i32 s86, 0, 0x10000
	s_cmp_eq_u32 s43, 12
	s_cselect_b32 s39, s19, s37
	s_cselect_b32 s38, s25, s36
	s_cselect_b32 s37, s0, s77
	s_cselect_b32 s36, s17, s76
	s_add_i32 s76, 0, 0x14000
	ds_read_b128 v[96:99], v186
	ds_read_b128 v[150:153], v186 offset:1024
	ds_read_b128 v[154:157], v186 offset:2048
	ds_read_b128 v[158:161], v186 offset:3072
	ds_read_b128 v[162:165], v186 offset:16384
	ds_read_b128 v[166:169], v186 offset:17408
	ds_read_b128 v[170:173], v186 offset:18432
	ds_read_b128 v[174:177], v186 offset:19456
	s_add_u32 s30, s28, s30
	s_addc_u32 s31, s29, s31
	s_add_u32 s30, s30, 0x40080
	s_addc_u32 s31, s31, 0
	s_add_i32 m0, s60, 0xc000
	ds_read_b128 v[178:181], v149
	ds_read_b128 v[182:185], v149 offset:1024
	ds_read_b128 v[202:205], v149 offset:2048
	ds_read_b128 v[206:209], v149 offset:3072
	ds_read_b128 v[210:213], v149 offset:4096
	ds_read_b128 v[214:217], v149 offset:5120
	ds_read_b128 v[218:221], v149 offset:6144
	ds_read_b128 v[222:225], v149 offset:7168
	global_load_lds_dwordx4 v136, s[30:31]
	s_add_i32 m0, s60, 0xe000
	s_nop 0
	global_load_lds_dwordx4 v134, s[30:31]
	s_waitcnt vmcnt(8)
	s_waitcnt lgkmcnt(0)
	s_barrier
	v_mfma_f32_16x16x32_bf16 v[128:131], v[96:99], v[178:181], v[128:131]
	v_mfma_f32_16x16x32_bf16 v[120:123], v[154:157], v[178:181], v[120:123]
	v_mfma_f32_16x16x32_bf16 v[112:115], v[96:99], v[202:205], v[112:115]
	v_mfma_f32_16x16x32_bf16 v[104:107], v[154:157], v[202:205], v[104:107]
	v_mfma_f32_16x16x32_bf16 v[92:95], v[96:99], v[210:213], v[92:95]
	v_mfma_f32_16x16x32_bf16 v[84:87], v[154:157], v[210:213], v[84:87]
	v_mfma_f32_16x16x32_bf16 v[76:79], v[96:99], v[218:221], v[76:79]
	v_mfma_f32_16x16x32_bf16 v[68:71], v[154:157], v[218:221], v[68:71]
	v_mfma_f32_16x16x32_bf16 v[128:131], v[150:153], v[182:185], v[128:131]
	v_mfma_f32_16x16x32_bf16 v[120:123], v[158:161], v[182:185], v[120:123]
	v_mfma_f32_16x16x32_bf16 v[112:115], v[150:153], v[206:209], v[112:115]
	v_mfma_f32_16x16x32_bf16 v[104:107], v[158:161], v[206:209], v[104:107]
	v_mfma_f32_16x16x32_bf16 v[92:95], v[150:153], v[214:217], v[92:95]
	v_mfma_f32_16x16x32_bf16 v[84:87], v[158:161], v[214:217], v[84:87]
	v_mfma_f32_16x16x32_bf16 v[76:79], v[150:153], v[222:225], v[76:79]
	v_mfma_f32_16x16x32_bf16 v[68:71], v[158:161], v[222:225], v[68:71]
	v_mfma_f32_16x16x32_bf16 v[124:127], v[162:165], v[178:181], v[124:127]
	v_mfma_f32_16x16x32_bf16 v[116:119], v[170:173], v[178:181], v[116:119]
	v_mfma_f32_16x16x32_bf16 v[108:111], v[162:165], v[202:205], v[108:111]
	v_mfma_f32_16x16x32_bf16 v[100:103], v[170:173], v[202:205], v[100:103]
	v_mfma_f32_16x16x32_bf16 v[88:91], v[162:165], v[210:213], v[88:91]
	v_mfma_f32_16x16x32_bf16 v[80:83], v[170:173], v[210:213], v[80:83]
	v_mfma_f32_16x16x32_bf16 v[72:75], v[162:165], v[218:221], v[72:75]
	v_mfma_f32_16x16x32_bf16 v[64:67], v[170:173], v[218:221], v[64:67]
	v_mfma_f32_16x16x32_bf16 v[124:127], v[166:169], v[182:185], v[124:127]
	v_mfma_f32_16x16x32_bf16 v[116:119], v[174:177], v[182:185], v[116:119]
	v_mfma_f32_16x16x32_bf16 v[108:111], v[166:169], v[206:209], v[108:111]
	v_mfma_f32_16x16x32_bf16 v[100:103], v[174:177], v[206:209], v[100:103]
	v_mfma_f32_16x16x32_bf16 v[88:91], v[166:169], v[214:217], v[88:91]
	v_mfma_f32_16x16x32_bf16 v[80:83], v[174:177], v[214:217], v[80:83]
	v_mfma_f32_16x16x32_bf16 v[72:75], v[166:169], v[222:225], v[72:75]
	v_mfma_f32_16x16x32_bf16 v[64:67], v[174:177], v[222:225], v[64:67]
	s_barrier
	s_add_i32 s30, s86, s56
	s_mov_b32 m0, s30
	ds_read_b128 v[178:181], v149 offset:16384
	ds_read_b128 v[182:185], v149 offset:17408
	ds_read_b128 v[202:205], v149 offset:18432
	ds_read_b128 v[206:209], v149 offset:19456
	ds_read_b128 v[210:213], v149 offset:20480
	ds_read_b128 v[214:217], v149 offset:21504
	ds_read_b128 v[218:221], v149 offset:22528
	ds_read_b128 v[222:225], v149 offset:23552
	global_load_lds_dwordx4 v188, s[36:37]
	s_add_i32 m0, s30, 0x2000
	s_add_u32 s30, s36, 0x40000
	s_addc_u32 s31, s37, 0
	s_add_i32 s76, s76, s56
	global_load_lds_dwordx4 v132, s[36:37]
	s_mov_b32 m0, s76
	s_nop 0
	global_load_lds_dwordx4 v188, s[30:31]
	s_add_i32 m0, s76, 0x2000
	s_nop 0
	global_load_lds_dwordx4 v132, s[30:31]
	s_mov_b32 m0, s60
	s_nop 0
	global_load_lds_dwordx4 v136, s[38:39]
	s_mov_b32 m0, s71
	s_nop 0
	global_load_lds_dwordx4 v134, s[38:39]
	s_waitcnt vmcnt(8)
	s_waitcnt lgkmcnt(0)
	s_barrier
	v_mfma_f32_16x16x32_bf16 v[60:63], v[96:99], v[178:181], v[60:63]
	v_mfma_f32_16x16x32_bf16 v[52:55], v[154:157], v[178:181], v[52:55]
	v_mfma_f32_16x16x32_bf16 v[44:47], v[96:99], v[202:205], v[44:47]
	v_mfma_f32_16x16x32_bf16 v[36:39], v[154:157], v[202:205], v[36:39]
	v_mfma_f32_16x16x32_bf16 v[28:31], v[96:99], v[210:213], v[28:31]
	v_mfma_f32_16x16x32_bf16 v[20:23], v[154:157], v[210:213], v[20:23]
	v_mfma_f32_16x16x32_bf16 v[12:15], v[96:99], v[218:221], v[12:15]
	v_mfma_f32_16x16x32_bf16 v[4:7], v[154:157], v[218:221], v[4:7]
	v_mfma_f32_16x16x32_bf16 v[60:63], v[150:153], v[182:185], v[60:63]
	v_mfma_f32_16x16x32_bf16 v[52:55], v[158:161], v[182:185], v[52:55]
	v_mfma_f32_16x16x32_bf16 v[44:47], v[150:153], v[206:209], v[44:47]
	v_mfma_f32_16x16x32_bf16 v[36:39], v[158:161], v[206:209], v[36:39]
	v_mfma_f32_16x16x32_bf16 v[28:31], v[150:153], v[214:217], v[28:31]
	v_mfma_f32_16x16x32_bf16 v[20:23], v[158:161], v[214:217], v[20:23]
	v_mfma_f32_16x16x32_bf16 v[12:15], v[150:153], v[222:225], v[12:15]
	v_mfma_f32_16x16x32_bf16 v[4:7], v[158:161], v[222:225], v[4:7]
	v_mfma_f32_16x16x32_bf16 v[56:59], v[162:165], v[178:181], v[56:59]
	v_mfma_f32_16x16x32_bf16 v[48:51], v[170:173], v[178:181], v[48:51]
	v_mfma_f32_16x16x32_bf16 v[40:43], v[162:165], v[202:205], v[40:43]
	v_mfma_f32_16x16x32_bf16 v[32:35], v[170:173], v[202:205], v[32:35]
	v_mfma_f32_16x16x32_bf16 v[24:27], v[162:165], v[210:213], v[24:27]
	v_mfma_f32_16x16x32_bf16 v[16:19], v[170:173], v[210:213], v[16:19]
	v_mfma_f32_16x16x32_bf16 v[8:11], v[162:165], v[218:221], v[8:11]
	v_mfma_f32_16x16x32_bf16 v[0:3], v[170:173], v[218:221], v[0:3]
	v_mfma_f32_16x16x32_bf16 v[56:59], v[166:169], v[182:185], v[56:59]
	v_mfma_f32_16x16x32_bf16 v[48:51], v[174:177], v[182:185], v[48:51]
	v_mfma_f32_16x16x32_bf16 v[40:43], v[166:169], v[206:209], v[40:43]
	v_mfma_f32_16x16x32_bf16 v[32:35], v[174:177], v[206:209], v[32:35]
	v_mfma_f32_16x16x32_bf16 v[24:27], v[166:169], v[214:217], v[24:27]
	v_mfma_f32_16x16x32_bf16 v[16:19], v[174:177], v[214:217], v[16:19]
	v_mfma_f32_16x16x32_bf16 v[8:11], v[166:169], v[222:225], v[8:11]
	v_mfma_f32_16x16x32_bf16 v[0:3], v[174:177], v[222:225], v[0:3]
	s_barrier
	s_add_i32 s76, 0, 0x18000
	s_add_i32 s77, 0, 0x1c000
	ds_read_b128 v[96:99], v186 offset:32768
	ds_read_b128 v[150:153], v186 offset:33792
	ds_read_b128 v[154:157], v186 offset:34816
	ds_read_b128 v[158:161], v186 offset:35840
	ds_read_b128 v[162:165], v186 offset:49152
	ds_read_b128 v[166:169], v186 offset:50176
	ds_read_b128 v[170:173], v186 offset:51200
	ds_read_b128 v[174:177], v186 offset:52224
	s_add_u32 s30, s38, 0x40000
	s_addc_u32 s31, s39, 0
	s_mov_b32 m0, s87
	ds_read_b128 v[178:181], v149 offset:32768
	ds_read_b128 v[182:185], v149 offset:33792
	ds_read_b128 v[202:205], v149 offset:34816
	ds_read_b128 v[206:209], v149 offset:35840
	ds_read_b128 v[210:213], v149 offset:36864
	ds_read_b128 v[214:217], v149 offset:37888
	ds_read_b128 v[218:221], v149 offset:38912
	ds_read_b128 v[222:225], v149 offset:39936
	global_load_lds_dwordx4 v136, s[30:31]
	s_mov_b32 m0, s89
	s_nop 0
	global_load_lds_dwordx4 v134, s[30:31]
	s_waitcnt vmcnt(8)
	s_waitcnt lgkmcnt(0)
	s_barrier
	v_mfma_f32_16x16x32_bf16 v[128:131], v[96:99], v[178:181], v[128:131]
	v_mfma_f32_16x16x32_bf16 v[120:123], v[154:157], v[178:181], v[120:123]
	v_mfma_f32_16x16x32_bf16 v[112:115], v[96:99], v[202:205], v[112:115]
	v_mfma_f32_16x16x32_bf16 v[104:107], v[154:157], v[202:205], v[104:107]
	v_mfma_f32_16x16x32_bf16 v[92:95], v[96:99], v[210:213], v[92:95]
	v_mfma_f32_16x16x32_bf16 v[84:87], v[154:157], v[210:213], v[84:87]
	v_mfma_f32_16x16x32_bf16 v[76:79], v[96:99], v[218:221], v[76:79]
	v_mfma_f32_16x16x32_bf16 v[68:71], v[154:157], v[218:221], v[68:71]
	v_mfma_f32_16x16x32_bf16 v[128:131], v[150:153], v[182:185], v[128:131]
	v_mfma_f32_16x16x32_bf16 v[120:123], v[158:161], v[182:185], v[120:123]
	v_mfma_f32_16x16x32_bf16 v[112:115], v[150:153], v[206:209], v[112:115]
	v_mfma_f32_16x16x32_bf16 v[104:107], v[158:161], v[206:209], v[104:107]
	v_mfma_f32_16x16x32_bf16 v[92:95], v[150:153], v[214:217], v[92:95]
	v_mfma_f32_16x16x32_bf16 v[84:87], v[158:161], v[214:217], v[84:87]
	v_mfma_f32_16x16x32_bf16 v[76:79], v[150:153], v[222:225], v[76:79]
	v_mfma_f32_16x16x32_bf16 v[68:71], v[158:161], v[222:225], v[68:71]
	v_mfma_f32_16x16x32_bf16 v[124:127], v[162:165], v[178:181], v[124:127]
	v_mfma_f32_16x16x32_bf16 v[116:119], v[170:173], v[178:181], v[116:119]
	v_mfma_f32_16x16x32_bf16 v[108:111], v[162:165], v[202:205], v[108:111]
	v_mfma_f32_16x16x32_bf16 v[100:103], v[170:173], v[202:205], v[100:103]
	v_mfma_f32_16x16x32_bf16 v[88:91], v[162:165], v[210:213], v[88:91]
	v_mfma_f32_16x16x32_bf16 v[80:83], v[170:173], v[210:213], v[80:83]
	v_mfma_f32_16x16x32_bf16 v[72:75], v[162:165], v[218:221], v[72:75]
	v_mfma_f32_16x16x32_bf16 v[64:67], v[170:173], v[218:221], v[64:67]
	v_mfma_f32_16x16x32_bf16 v[124:127], v[166:169], v[182:185], v[124:127]
	v_mfma_f32_16x16x32_bf16 v[116:119], v[174:177], v[182:185], v[116:119]
	v_mfma_f32_16x16x32_bf16 v[108:111], v[166:169], v[206:209], v[108:111]
	v_mfma_f32_16x16x32_bf16 v[100:103], v[174:177], v[206:209], v[100:103]
	v_mfma_f32_16x16x32_bf16 v[88:91], v[166:169], v[214:217], v[88:91]
	v_mfma_f32_16x16x32_bf16 v[80:83], v[174:177], v[214:217], v[80:83]
	v_mfma_f32_16x16x32_bf16 v[72:75], v[166:169], v[222:225], v[72:75]
	v_mfma_f32_16x16x32_bf16 v[64:67], v[174:177], v[222:225], v[64:67]
	s_barrier
	s_add_i32 s30, s76, s56
	s_add_u32 s100, s36, 0x80
	s_addc_u32 s101, s37, 0
	s_mov_b32 m0, s30
	ds_read_b128 v[178:181], v149 offset:49152
	ds_read_b128 v[182:185], v149 offset:50176
	ds_read_b128 v[202:205], v149 offset:51200
	ds_read_b128 v[206:209], v149 offset:52224
	ds_read_b128 v[210:213], v149 offset:53248
	ds_read_b128 v[214:217], v149 offset:54272
	ds_read_b128 v[218:221], v149 offset:55296
	ds_read_b128 v[222:225], v149 offset:56320
	global_load_lds_dwordx4 v188, s[100:101]
	s_add_i32 m0, s30, 0x2000
	s_add_u32 s30, s36, 0x40080
	s_addc_u32 s31, s37, 0
	s_add_i32 s36, s77, s56
	global_load_lds_dwordx4 v132, s[100:101]
	s_mov_b32 m0, s36
	s_nop 0
	global_load_lds_dwordx4 v188, s[30:31]
	s_add_i32 m0, s36, 0x2000
	s_nop 0
	global_load_lds_dwordx4 v132, s[30:31]
	s_add_u32 s100, s38, 0x80
	s_addc_u32 s101, s39, 0
	s_mov_b32 m0, s90
	s_nop 0
	global_load_lds_dwordx4 v136, s[100:101]
	s_mov_b32 m0, s91
	s_nop 0
	global_load_lds_dwordx4 v134, s[100:101]
	s_waitcnt vmcnt(8)
	s_waitcnt lgkmcnt(0)
	s_barrier
	v_mfma_f32_16x16x32_bf16 v[60:63], v[96:99], v[178:181], v[60:63]
	v_mfma_f32_16x16x32_bf16 v[52:55], v[154:157], v[178:181], v[52:55]
	v_mfma_f32_16x16x32_bf16 v[44:47], v[96:99], v[202:205], v[44:47]
	v_mfma_f32_16x16x32_bf16 v[36:39], v[154:157], v[202:205], v[36:39]
	v_mfma_f32_16x16x32_bf16 v[28:31], v[96:99], v[210:213], v[28:31]
	v_mfma_f32_16x16x32_bf16 v[20:23], v[154:157], v[210:213], v[20:23]
	v_mfma_f32_16x16x32_bf16 v[12:15], v[96:99], v[218:221], v[12:15]
	v_mfma_f32_16x16x32_bf16 v[4:7], v[154:157], v[218:221], v[4:7]
	v_mfma_f32_16x16x32_bf16 v[60:63], v[150:153], v[182:185], v[60:63]
	v_mfma_f32_16x16x32_bf16 v[52:55], v[158:161], v[182:185], v[52:55]
	v_mfma_f32_16x16x32_bf16 v[44:47], v[150:153], v[206:209], v[44:47]
	v_mfma_f32_16x16x32_bf16 v[36:39], v[158:161], v[206:209], v[36:39]
	v_mfma_f32_16x16x32_bf16 v[28:31], v[150:153], v[214:217], v[28:31]
	v_mfma_f32_16x16x32_bf16 v[20:23], v[158:161], v[214:217], v[20:23]
	v_mfma_f32_16x16x32_bf16 v[12:15], v[150:153], v[222:225], v[12:15]
	v_mfma_f32_16x16x32_bf16 v[4:7], v[158:161], v[222:225], v[4:7]
	v_mfma_f32_16x16x32_bf16 v[56:59], v[162:165], v[178:181], v[56:59]
	v_mfma_f32_16x16x32_bf16 v[48:51], v[170:173], v[178:181], v[48:51]
	v_mfma_f32_16x16x32_bf16 v[40:43], v[162:165], v[202:205], v[40:43]
	v_mfma_f32_16x16x32_bf16 v[32:35], v[170:173], v[202:205], v[32:35]
	v_mfma_f32_16x16x32_bf16 v[24:27], v[162:165], v[210:213], v[24:27]
	v_mfma_f32_16x16x32_bf16 v[16:19], v[170:173], v[210:213], v[16:19]
	v_mfma_f32_16x16x32_bf16 v[8:11], v[162:165], v[218:221], v[8:11]
	v_mfma_f32_16x16x32_bf16 v[0:3], v[170:173], v[218:221], v[0:3]
	v_mfma_f32_16x16x32_bf16 v[56:59], v[166:169], v[182:185], v[56:59]
	v_mfma_f32_16x16x32_bf16 v[48:51], v[174:177], v[182:185], v[48:51]
	v_mfma_f32_16x16x32_bf16 v[40:43], v[166:169], v[206:209], v[40:43]
	v_mfma_f32_16x16x32_bf16 v[32:35], v[174:177], v[206:209], v[32:35]
	v_mfma_f32_16x16x32_bf16 v[24:27], v[166:169], v[214:217], v[24:27]
	v_mfma_f32_16x16x32_bf16 v[16:19], v[174:177], v[214:217], v[16:19]
	v_mfma_f32_16x16x32_bf16 v[8:11], v[166:169], v[222:225], v[8:11]
	v_mfma_f32_16x16x32_bf16 v[0:3], v[174:177], v[222:225], v[0:3]
	s_barrier
	s_add_i32 s43, s43, 2
	s_cmp_gt_u32 s43, 13
	s_mov_b64 s[30:31], s[34:35]
	s_cbranch_scc0 .LBB0_528
